# first phase seam uses the two-level XCD barrier instead of cooperative-groups grid sync; attention loop hazard margin
# speedup vs baseline: 1.0079x; 1.0079x over previous
; #define LAS __attribute__((address_space(3)))
; __device__ __forceinline__ void attn_block(LAS unsigned char* lds, const bf16_t* P, bf16_t* mix, int b, int h, int qb, float lam, float outscale, const float* subln) {
;     ...
;     for (int kt = 0; kt < ntiles; ++kt) {
;         __syncthreads();
;         const int buf = kt & 1;
;         if (kt + 1 < ntiles) {
;             const size_t ro = (size_t)(64 * (kt + 1)) * INC;
;             kr0 = *(const u32x4*)(kg + ro + (size_t)srow * INC); kr1 = *(const u32x4*)(kg + ro + (size_t)(srow + 32) * INC);
;             vr0 = *(const u32x4*)(vg + ro + (size_t)srow * INC); vr1 = *(const u32x4*)(vg + ro + (size_t)(srow + 32) * INC);
;         }
;         const int kb = 64 * kt;
;         if (kb <= qw0 + 31) {
;             LAS const unsigned char* Kb = lds + ATT_K0 + buf * 16384;
;             LAS const unsigned char* Vb = lds + ATT_V0 + buf * 16384;
;             f32x16 s0, s1;
; #pragma unroll
;             for (int j = 0; j < 16; ++j) { s0[j] = 0.f; s1[j] = 0.f; }
;             bf16x8 ka[4][2];
; #pragma unroll
;             for (int ks = 0; ks < 4; ++ks) { ka[ks][0] = *(const LAS bf16x8*)(Kb + kbase[ks]); ka[ks][1] = *(const LAS bf16x8*)(Kb + kbase[ks] + 8192); }
;             __builtin_amdgcn_sched_barrier(0);
; #pragma unroll
;             for (int ks = 0; ks < 4; ++ks) {
;                 s0 = __builtin_amdgcn_mfma_f32_32x32x16_bf16(ka[ks][0], qf[ks], s0, 0, 0, 0);
;                 s1 = __builtin_amdgcn_mfma_f32_32x32x16_bf16(ka[ks][1], qf[ks], s1, 0, 0, 0);
;             }
;             if (kb + 63 > qw0) {
; #pragma unroll
;                 for (int j = 0; j < 16; ++j) { const int key = kb + crow(j, hi); if (key > qrow) s0[j] = -INFINITY; if (key + 32 > qrow) s1[j] = -INFINITY; }
;             }
;             float mxa = max3f(s0[0], s1[0], s0[1]), mxb = max3f(s1[1], s0[2], s1[2]), mxc = max3f(s0[3], s1[3], s0[4]), mxd = max3f(s1[4], s0[5], s1[5]);
;             mxa = max3f(mxa, s0[6], s1[6]); mxb = max3f(mxb, s0[7], s1[7]); mxc = max3f(mxc, s0[8], s1[8]); mxd = max3f(mxd, s0[9], s1[9]);
;             mxa = max3f(mxa, s0[10], s1[10]); mxb = max3f(mxb, s0[11], s1[11]); mxc = max3f(mxc, s0[12], s1[12]); mxd = max3f(mxd, s0[13], s1[13]);
;             mxa = max3f(mxa, s0[14], s1[14]); mxb = max3f(mxb, s0[15], s1[15]);
;             float mx = max3f(mxa, mxb, max3f(mxc, mxd, mxd));
.Lat1_U_top:
	s_add_i32 m0, s73, 0x14000
	s_nop 0
	global_load_lds_dwordx4 v[134:135], off
	s_add_i32 m0, s73, 0x16000
	s_nop 0
	global_load_lds_dwordx4 v[200:201], off
	s_waitcnt lgkmcnt(6)
	v_mfma_f32_32x32x16_bf16 v[82:97], v[136:139], v[110:113], v[222:237]
	v_mfma_f32_32x32x16_bf16 v[66:81], v[140:143], v[110:113], v[222:237]
	s_waitcnt lgkmcnt(4)
	v_mfma_f32_32x32x16_bf16 v[82:97], v[204:207], v[106:109], v[82:97]
	v_mfma_f32_32x32x16_bf16 v[66:81], v[208:211], v[106:109], v[66:81]
	s_waitcnt lgkmcnt(2)
	v_mfma_f32_32x32x16_bf16 v[82:97], v[238:241], v[102:105], v[82:97]
	v_mfma_f32_32x32x16_bf16 v[66:81], v[242:245], v[102:105], v[66:81]
	s_waitcnt lgkmcnt(0)
	v_mfma_f32_32x32x16_bf16 v[82:97], v[246:249], v[98:101], v[82:97]
	v_mfma_f32_32x32x16_bf16 v[66:81], v[250:253], v[98:101], v[66:81]
	ds_read_b64_tr_b16 v[136:137], v173 offset:32768
	ds_read_b64_tr_b16 v[138:139], v174 offset:32768
	ds_read_b64_tr_b16 v[140:141], v170 offset:32768
	ds_read_b64_tr_b16 v[142:143], v172 offset:32768
	ds_read_b64_tr_b16 v[204:205], v168 offset:32768
	ds_read_b64_tr_b16 v[206:207], v171 offset:32768
	ds_read_b64_tr_b16 v[208:209], v145 offset:32768
	ds_read_b64_tr_b16 v[210:211], v169 offset:32768
	ds_read_b64_tr_b16 v[238:239], v173 offset:36864
	ds_read_b64_tr_b16 v[240:241], v174 offset:36864
	ds_read_b64_tr_b16 v[242:243], v170 offset:36864
	ds_read_b64_tr_b16 v[244:245], v172 offset:36864
	s_nop 1
	v_max3_f32 v122, v82, v66, v83
	v_max3_f32 v123, v67, v84, v68
	v_max3_f32 v124, v85, v69, v86
	v_max3_f32 v125, v70, v87, v71
	v_max3_f32 v122, v122, v88, v72
	v_max3_f32 v123, v123, v89, v73
	v_max3_f32 v124, v124, v90, v74
	v_max3_f32 v125, v125, v91, v75
	v_max3_f32 v122, v122, v92, v76
	v_max3_f32 v123, v123, v93, v77
	v_max3_f32 v124, v124, v94, v78
	v_max3_f32 v125, v125, v95, v79
	v_max3_f32 v122, v122, v96, v80
	v_max3_f32 v123, v123, v97, v81
	v_max3_f32 v122, v122, v123, v124
	v_max_f32_e32 v122, v122, v125
	v_mov_b32_e32 v203, v122
	s_nop 1
	v_permlane32_swap_b32_e32 v122, v203
	s_nop 1
	v_max_f32_e32 v122, v122, v203
	s_mov_b32 s70, 0
	v_cmp_lt_f32_e32 vcc, 0x41000000, v122
	s_cmp_eq_u32 s71, 0
	s_cbranch_scc1 .Lat1_u0_first
	s_cbranch_vccz .Lat1_u0_norescale
	s_branch .Lat1_u0_rescale

; #define LAS __attribute__((address_space(3)))
; __device__ __forceinline__ unsigned pk2(float lo, float hi) { f32x2 v = {lo, hi}; bf16x2_t b = __builtin_convertvector(v, bf16x2_t); return __builtin_bit_cast(unsigned, b); }
; __device__ __forceinline__ s16x4 vtr(LAS const unsigned char* p) { return __builtin_bit_cast(s16x4, __builtin_amdgcn_ds_read_tr16_b64_v4i16((LAS v4i16_t*)p)); }
; __device__ __forceinline__ bf16x8 cat8(s16x4 a, s16x4 b) { return (bf16x8){a[0], a[1], a[2], a[3], b[0], b[1], b[2], b[3]}; }
; __device__ __forceinline__ void attn_block(LAS unsigned char* lds, const bf16_t* P, bf16_t* mix, int b, int h, int qb, float lam, float outscale, const float* subln) {
;     ...
;             for (int ks = 0; ks < 4; ++ks) { ka[ks][0] = *(const LAS bf16x8*)(Kb + kbase[ks]); ka[ks][1] = *(const LAS bf16x8*)(Kb + kbase[ks] + 8192); }
;     ...
; #pragma unroll
;             for (int j = 0; j < 16; ++j) { s0[j] = __builtin_amdgcn_exp2f(s0[j] - mrun); s1[j] = __builtin_amdgcn_exp2f(s1[j] - mrun); }
;             float ps0 = 0.f, ps1 = 0.f, ps2 = 0.f, ps3 = 0.f;
; #pragma unroll
;             for (int j = 0; j < 16; j += 2) { ps0 += s0[j]; ps1 += s1[j]; ps2 += s0[j + 1]; ps3 += s1[j + 1]; }
;             lrun += (ps0 + ps1) + (ps2 + ps3);
;             bf16x8 pb[4];
; #pragma unroll
;             for (int s2 = 0; s2 < 2; ++s2) {
;                 u32x4 w0, w1;
;                 w0.x = pk2(s0[8 * s2 + 0], s0[8 * s2 + 1]); w0.y = pk2(s0[8 * s2 + 2], s0[8 * s2 + 3]); w0.z = pk2(s0[8 * s2 + 4], s0[8 * s2 + 5]); w0.w = pk2(s0[8 * s2 + 6], s0[8 * s2 + 7]);
;                 w1.x = pk2(s1[8 * s2 + 0], s1[8 * s2 + 1]); w1.y = pk2(s1[8 * s2 + 2], s1[8 * s2 + 3]); w1.z = pk2(s1[8 * s2 + 4], s1[8 * s2 + 5]); w1.w = pk2(s1[8 * s2 + 6], s1[8 * s2 + 7]);
;                 pb[s2] = __builtin_bit_cast(bf16x8, w0); pb[2 + s2] = __builtin_bit_cast(bf16x8, w1);
;             }
; #pragma unroll
;             for (int s = 0; s < 4; ++s) {
; #pragma unroll
;                 for (int c = 0; c < 4; ++c) {
;                     const s16x4 v0 = vtr(Vb + vbase[c][0] + 4096 * s);
;                     const s16x4 v1 = vtr(Vb + vbase[c][1] + 4096 * s);
;                     o[c] = __builtin_amdgcn_mfma_f32_32x32x16_bf16(cat8(v0, v1), pb[s], o[c], 0, 0, 0);
;                 }
;             }
.Lat1_u0_norescale:
	v_exp_f32_e32 v82, v82
	v_exp_f32_e32 v83, v83
	v_exp_f32_e32 v84, v84
	v_exp_f32_e32 v85, v85
	v_exp_f32_e32 v86, v86
	v_exp_f32_e32 v87, v87
	v_exp_f32_e32 v88, v88
	v_exp_f32_e32 v89, v89
	v_exp_f32_e32 v90, v90
	v_exp_f32_e32 v91, v91
	v_exp_f32_e32 v92, v92
	v_exp_f32_e32 v93, v93
	v_exp_f32_e32 v94, v94
	v_exp_f32_e32 v95, v95
	v_exp_f32_e32 v96, v96
	v_exp_f32_e32 v97, v97
	v_cvt_pk_bf16_f32 v184, v82, v83
	v_cvt_pk_bf16_f32 v185, v84, v85
	v_cvt_pk_bf16_f32 v186, v86, v87
	v_cvt_pk_bf16_f32 v187, v88, v89
	v_cvt_pk_bf16_f32 v188, v90, v91
	v_cvt_pk_bf16_f32 v189, v92, v93
	v_cvt_pk_bf16_f32 v190, v94, v95
	v_cvt_pk_bf16_f32 v191, v96, v97
	v_add_f32_e32 v122, v82, v83
	v_add_f32_e32 v123, v84, v85
	v_add_f32_e32 v122, v122, v86
	v_add_f32_e32 v123, v123, v87
	v_add_f32_e32 v122, v122, v88
	v_add_f32_e32 v123, v123, v89
	v_add_f32_e32 v122, v122, v123
	v_add_f32_e32 v167, v167, v122
	v_add_f32_e32 v124, v90, v91
	v_add_f32_e32 v125, v92, v93
	v_add_f32_e32 v124, v124, v94
	v_add_f32_e32 v125, v125, v95
	v_add_f32_e32 v124, v124, v96
	v_add_f32_e32 v125, v125, v97
	v_add_f32_e32 v124, v124, v125
	v_add_f32_e32 v167, v167, v124
	s_add_i32 m0, s73, 0x1b800
	s_nop 0
	global_load_lds_dwordx4 v[134:135], off offset:2048
	s_add_i32 m0, s73, 0x1d800
	s_nop 0
	global_load_lds_dwordx4 v[200:201], off offset:2048
	v_lshl_add_u64 v[134:135], v[134:135], 0, s[40:41]
	v_lshl_add_u64 v[200:201], v[200:201], 0, s[40:41]
	s_waitcnt lgkmcnt(8)
	v_mfma_f32_32x32x16_bf16 v[50:65], v[136:139], v[184:187], v[50:65]
	ds_read_b64_tr_b16 v[246:247], v168 offset:36864
	ds_read_b64_tr_b16 v[248:249], v171 offset:36864
	v_exp_f32_e32 v66, v66
	v_exp_f32_e32 v67, v67
	v_exp_f32_e32 v68, v68
	v_mfma_f32_32x32x16_bf16 v[34:49], v[140:143], v[184:187], v[34:49]
	ds_read_b64_tr_b16 v[250:251], v145 offset:36864
	ds_read_b64_tr_b16 v[252:253], v169 offset:36864
	v_exp_f32_e32 v69, v69
	v_exp_f32_e32 v70, v70
	v_exp_f32_e32 v71, v71
	s_waitcnt lgkmcnt(8)
	v_mfma_f32_32x32x16_bf16 v[18:33], v[204:207], v[184:187], v[18:33]
	ds_read_b64_tr_b16 v[136:137], v173 offset:40960
	ds_read_b64_tr_b16 v[138:139], v174 offset:40960
	v_exp_f32_e32 v72, v72
	v_exp_f32_e32 v73, v73
	v_cvt_pk_bf16_f32 v192, v66, v67
	v_mfma_f32_32x32x16_bf16 v[2:17], v[208:211], v[184:187], v[2:17]
	ds_read_b64_tr_b16 v[140:141], v170 offset:40960
	ds_read_b64_tr_b16 v[142:143], v172 offset:40960
	v_cvt_pk_bf16_f32 v193, v68, v69
	v_cvt_pk_bf16_f32 v194, v70, v71
	v_cvt_pk_bf16_f32 v195, v72, v73
	s_waitcnt lgkmcnt(8)
	v_mfma_f32_32x32x16_bf16 v[50:65], v[238:241], v[188:191], v[50:65]
	ds_read_b64_tr_b16 v[204:205], v168 offset:40960
	ds_read_b64_tr_b16 v[206:207], v171 offset:40960
	v_exp_f32_e32 v74, v74
	v_exp_f32_e32 v75, v75
	v_exp_f32_e32 v76, v76
	v_mfma_f32_32x32x16_bf16 v[34:49], v[242:245], v[188:191], v[34:49]
	ds_read_b64_tr_b16 v[208:209], v145 offset:40960
	ds_read_b64_tr_b16 v[210:211], v169 offset:40960
	v_exp_f32_e32 v77, v77
	v_exp_f32_e32 v78, v78
	v_exp_f32_e32 v79, v79
	s_waitcnt lgkmcnt(8)
	v_mfma_f32_32x32x16_bf16 v[18:33], v[246:249], v[188:191], v[18:33]
	ds_read_b64_tr_b16 v[238:239], v173 offset:45056
	ds_read_b64_tr_b16 v[240:241], v174 offset:45056
	v_exp_f32_e32 v80, v80
	v_exp_f32_e32 v81, v81
	v_cvt_pk_bf16_f32 v196, v74, v75
	v_mfma_f32_32x32x16_bf16 v[2:17], v[250:253], v[188:191], v[2:17]
	ds_read_b64_tr_b16 v[242:243], v170 offset:45056
	ds_read_b64_tr_b16 v[244:245], v172 offset:45056
	v_cvt_pk_bf16_f32 v197, v76, v77
	v_cvt_pk_bf16_f32 v198, v78, v79
	v_cvt_pk_bf16_f32 v199, v80, v81
	s_waitcnt lgkmcnt(8)
	v_mfma_f32_32x32x16_bf16 v[50:65], v[136:139], v[192:195], v[50:65]
	ds_read_b64_tr_b16 v[246:247], v168 offset:45056
	ds_read_b64_tr_b16 v[248:249], v171 offset:45056
	v_add_f32_e32 v0, v66, v67
	v_add_f32_e32 v203, v68, v69
	v_add_f32_e32 v0, v0, v70
	v_mfma_f32_32x32x16_bf16 v[34:49], v[140:143], v[192:195], v[34:49]
	ds_read_b64_tr_b16 v[250:251], v145 offset:45056
	ds_read_b64_tr_b16 v[252:253], v169 offset:45056
	v_add_f32_e32 v203, v203, v71
	v_add_f32_e32 v0, v0, v72
	v_add_f32_e32 v203, v203, v73
	s_waitcnt lgkmcnt(8)
	v_mfma_f32_32x32x16_bf16 v[18:33], v[204:207], v[192:195], v[18:33]
	v_add_f32_e32 v0, v0, v203
	v_add_f32_e32 v167, v167, v0
	v_add_f32_e32 v0, v74, v75
	v_mfma_f32_32x32x16_bf16 v[2:17], v[208:211], v[192:195], v[2:17]
	v_add_f32_e32 v203, v76, v77
	v_add_f32_e32 v0, v0, v78
	v_add_f32_e32 v203, v203, v79
	s_waitcnt lgkmcnt(4)
	v_mfma_f32_32x32x16_bf16 v[50:65], v[238:241], v[196:199], v[50:65]
	v_add_f32_e32 v0, v0, v80
	v_add_f32_e32 v203, v203, v81
	v_add_f32_e32 v0, v0, v203
	v_mfma_f32_32x32x16_bf16 v[34:49], v[242:245], v[196:199], v[34:49]
	v_add_f32_e32 v167, v167, v0
	s_waitcnt lgkmcnt(0)
	v_mfma_f32_32x32x16_bf16 v[18:33], v[246:249], v[196:199], v[18:33]
	v_mfma_f32_32x32x16_bf16 v[2:17], v[250:253], v[196:199], v[2:17]
	ds_read_b128 v[136:139], v180 offset:16384
	ds_read_b128 v[140:143], v180 offset:24576
	ds_read_b128 v[204:207], v181 offset:16384
	ds_read_b128 v[208:211], v181 offset:24576
	ds_read_b128 v[238:241], v178 offset:16384
	ds_read_b128 v[242:245], v178 offset:24576
	ds_read_b128 v[246:249], v177 offset:16384
	ds_read_b128 v[250:253], v177 offset:24576
	s_waitcnt vmcnt(6)
	s_add_i32 s71, s71, 64
	s_barrier
; #define LAS __attribute__((address_space(3)))
; __device__ __forceinline__ float max3f(float a, float b, float c) { float r; asm("v_max3_f32 %0, %1, %2, %3" : "=v"(r) : "v"(a), "v"(b), "v"(c)); return r; }
; __device__ __forceinline__ void attn_block(LAS unsigned char* lds, const bf16_t* P, bf16_t* mix, int b, int h, int qb, float lam, float outscale, const float* subln) {
;     ...
;         const int kb = 64 * kt;
;         if (kb <= qw0 + 31) {
;             LAS const unsigned char* Kb = lds + ATT_K0 + buf * 16384;
;             LAS const unsigned char* Vb = lds + ATT_V0 + buf * 16384;
;             f32x16 s0, s1;
; #pragma unroll
;             for (int j = 0; j < 16; ++j) { s0[j] = 0.f; s1[j] = 0.f; }
;             bf16x8 ka[4][2];
; #pragma unroll
;             for (int ks = 0; ks < 4; ++ks) { ka[ks][0] = *(const LAS bf16x8*)(Kb + kbase[ks]); ka[ks][1] = *(const LAS bf16x8*)(Kb + kbase[ks] + 8192); }
;             __builtin_amdgcn_sched_barrier(0);
; #pragma unroll
;             for (int ks = 0; ks < 4; ++ks) {
;                 s0 = __builtin_amdgcn_mfma_f32_32x32x16_bf16(ka[ks][0], qf[ks], s0, 0, 0, 0);
;                 s1 = __builtin_amdgcn_mfma_f32_32x32x16_bf16(ka[ks][1], qf[ks], s1, 0, 0, 0);
;             }
;             if (kb + 63 > qw0) {
; #pragma unroll
;                 for (int j = 0; j < 16; ++j) { const int key = kb + crow(j, hi); if (key > qrow) s0[j] = -INFINITY; if (key + 32 > qrow) s1[j] = -INFINITY; }
;             }
;             float mxa = max3f(s0[0], s1[0], s0[1]), mxb = max3f(s1[1], s0[2], s1[2]), mxc = max3f(s0[3], s1[3], s0[4]), mxd = max3f(s1[4], s0[5], s1[5]);
;             mxa = max3f(mxa, s0[6], s1[6]); mxb = max3f(mxb, s0[7], s1[7]); mxc = max3f(mxc, s0[8], s1[8]); mxd = max3f(mxd, s0[9], s1[9]);
;             mxa = max3f(mxa, s0[10], s1[10]); mxb = max3f(mxb, s0[11], s1[11]); mxc = max3f(mxc, s0[12], s1[12]); mxd = max3f(mxd, s0[13], s1[13]);
;             mxa = max3f(mxa, s0[14], s1[14]); mxb = max3f(mxb, s0[15], s1[15]);
;             float mx = max3f(mxa, mxb, max3f(mxc, mxd, mxd));
;             { auto rr = __builtin_amdgcn_permlane32_swap(__builtin_bit_cast(unsigned, mx), __builtin_bit_cast(unsigned, mx), false, false);
;               mx = fmaxf(__builtin_bit_cast(float, rr[0]), __builtin_bit_cast(float, rr[1])); }
;             if (__any(mx > mrun + 8.0f)) {
	s_add_i32 m0, s73, 0x0
	s_nop 0
	global_load_lds_dwordx4 v[134:135], off
	s_add_i32 m0, s73, 0x2000
	s_nop 0
	global_load_lds_dwordx4 v[200:201], off
	s_waitcnt lgkmcnt(6)
	v_mfma_f32_32x32x16_bf16 v[82:97], v[136:139], v[110:113], v[222:237]
	v_mfma_f32_32x32x16_bf16 v[66:81], v[140:143], v[110:113], v[222:237]
	s_waitcnt lgkmcnt(4)
	v_mfma_f32_32x32x16_bf16 v[82:97], v[204:207], v[106:109], v[82:97]
	v_mfma_f32_32x32x16_bf16 v[66:81], v[208:211], v[106:109], v[66:81]
	s_waitcnt lgkmcnt(2)
	v_mfma_f32_32x32x16_bf16 v[82:97], v[238:241], v[102:105], v[82:97]
	v_mfma_f32_32x32x16_bf16 v[66:81], v[242:245], v[102:105], v[66:81]
	s_waitcnt lgkmcnt(0)
	v_mfma_f32_32x32x16_bf16 v[82:97], v[246:249], v[98:101], v[82:97]
	v_mfma_f32_32x32x16_bf16 v[66:81], v[250:253], v[98:101], v[66:81]
	ds_read_b64_tr_b16 v[136:137], v173 offset:49152
	ds_read_b64_tr_b16 v[138:139], v174 offset:49152
	ds_read_b64_tr_b16 v[140:141], v170 offset:49152
	ds_read_b64_tr_b16 v[142:143], v172 offset:49152
	ds_read_b64_tr_b16 v[204:205], v168 offset:49152
	ds_read_b64_tr_b16 v[206:207], v171 offset:49152
	ds_read_b64_tr_b16 v[208:209], v145 offset:49152
	ds_read_b64_tr_b16 v[210:211], v169 offset:49152
	ds_read_b64_tr_b16 v[238:239], v173 offset:53248
	ds_read_b64_tr_b16 v[240:241], v174 offset:53248
	ds_read_b64_tr_b16 v[242:243], v170 offset:53248
	ds_read_b64_tr_b16 v[244:245], v172 offset:53248
	s_nop 1
	v_max3_f32 v122, v82, v66, v83
	v_max3_f32 v123, v67, v84, v68
	v_max3_f32 v124, v85, v69, v86
	v_max3_f32 v125, v70, v87, v71
	v_max3_f32 v122, v122, v88, v72
	v_max3_f32 v123, v123, v89, v73
	v_max3_f32 v124, v124, v90, v74
	v_max3_f32 v125, v125, v91, v75
	v_max3_f32 v122, v122, v92, v76
	v_max3_f32 v123, v123, v93, v77
	v_max3_f32 v124, v124, v94, v78
	v_max3_f32 v125, v125, v95, v79
	v_max3_f32 v122, v122, v96, v80
	v_max3_f32 v123, v123, v97, v81
	v_max3_f32 v122, v122, v123, v124
	v_max_f32_e32 v122, v122, v125
	v_mov_b32_e32 v203, v122
	s_nop 1
	v_permlane32_swap_b32_e32 v122, v203
	s_nop 1
	v_max_f32_e32 v122, v122, v203
	s_mov_b32 s70, 0
	v_cmp_lt_f32_e32 vcc, 0x41000000, v122
	s_cmp_eq_u32 s71, 0
	s_cbranch_scc1 .Lat1_u1_first
	s_cbranch_vccz .Lat1_u1_norescale
	s_branch .Lat1_u1_rescale

; #define LAS __attribute__((address_space(3)))
; __device__ __forceinline__ unsigned pk2(float lo, float hi) { f32x2 v = {lo, hi}; bf16x2_t b = __builtin_convertvector(v, bf16x2_t); return __builtin_bit_cast(unsigned, b); }
; __device__ __forceinline__ s16x4 vtr(LAS const unsigned char* p) { return __builtin_bit_cast(s16x4, __builtin_amdgcn_ds_read_tr16_b64_v4i16((LAS v4i16_t*)p)); }
; __device__ __forceinline__ bf16x8 cat8(s16x4 a, s16x4 b) { return (bf16x8){a[0], a[1], a[2], a[3], b[0], b[1], b[2], b[3]}; }
; __device__ __forceinline__ void attn_block(LAS unsigned char* lds, const bf16_t* P, bf16_t* mix, int b, int h, int qb, float lam, float outscale, const float* subln) {
;     ...
;             for (int ks = 0; ks < 4; ++ks) { ka[ks][0] = *(const LAS bf16x8*)(Kb + kbase[ks]); ka[ks][1] = *(const LAS bf16x8*)(Kb + kbase[ks] + 8192); }
;     ...
; #pragma unroll
;             for (int j = 0; j < 16; ++j) { s0[j] = __builtin_amdgcn_exp2f(s0[j] - mrun); s1[j] = __builtin_amdgcn_exp2f(s1[j] - mrun); }
;             float ps0 = 0.f, ps1 = 0.f, ps2 = 0.f, ps3 = 0.f;
; #pragma unroll
;             for (int j = 0; j < 16; j += 2) { ps0 += s0[j]; ps1 += s1[j]; ps2 += s0[j + 1]; ps3 += s1[j + 1]; }
;             lrun += (ps0 + ps1) + (ps2 + ps3);
;             bf16x8 pb[4];
; #pragma unroll
;             for (int s2 = 0; s2 < 2; ++s2) {
;                 u32x4 w0, w1;
;                 w0.x = pk2(s0[8 * s2 + 0], s0[8 * s2 + 1]); w0.y = pk2(s0[8 * s2 + 2], s0[8 * s2 + 3]); w0.z = pk2(s0[8 * s2 + 4], s0[8 * s2 + 5]); w0.w = pk2(s0[8 * s2 + 6], s0[8 * s2 + 7]);
;                 w1.x = pk2(s1[8 * s2 + 0], s1[8 * s2 + 1]); w1.y = pk2(s1[8 * s2 + 2], s1[8 * s2 + 3]); w1.z = pk2(s1[8 * s2 + 4], s1[8 * s2 + 5]); w1.w = pk2(s1[8 * s2 + 6], s1[8 * s2 + 7]);
;                 pb[s2] = __builtin_bit_cast(bf16x8, w0); pb[2 + s2] = __builtin_bit_cast(bf16x8, w1);
;             }
; #pragma unroll
;             for (int s = 0; s < 4; ++s) {
; #pragma unroll
;                 for (int c = 0; c < 4; ++c) {
;                     const s16x4 v0 = vtr(Vb + vbase[c][0] + 4096 * s);
;                     const s16x4 v1 = vtr(Vb + vbase[c][1] + 4096 * s);
;                     o[c] = __builtin_amdgcn_mfma_f32_32x32x16_bf16(cat8(v0, v1), pb[s], o[c], 0, 0, 0);
;                 }
;             }
.Lat1_u1_norescale:
	v_exp_f32_e32 v82, v82
	v_exp_f32_e32 v83, v83
	v_exp_f32_e32 v84, v84
	v_exp_f32_e32 v85, v85
	v_exp_f32_e32 v86, v86
	v_exp_f32_e32 v87, v87
	v_exp_f32_e32 v88, v88
	v_exp_f32_e32 v89, v89
	v_exp_f32_e32 v90, v90
	v_exp_f32_e32 v91, v91
	v_exp_f32_e32 v92, v92
	v_exp_f32_e32 v93, v93
	v_exp_f32_e32 v94, v94
	v_exp_f32_e32 v95, v95
	v_exp_f32_e32 v96, v96
	v_exp_f32_e32 v97, v97
	v_cvt_pk_bf16_f32 v184, v82, v83
	v_cvt_pk_bf16_f32 v185, v84, v85
	v_cvt_pk_bf16_f32 v186, v86, v87
	v_cvt_pk_bf16_f32 v187, v88, v89
	v_cvt_pk_bf16_f32 v188, v90, v91
	v_cvt_pk_bf16_f32 v189, v92, v93
	v_cvt_pk_bf16_f32 v190, v94, v95
	v_cvt_pk_bf16_f32 v191, v96, v97
	v_add_f32_e32 v122, v82, v83
	v_add_f32_e32 v123, v84, v85
	v_add_f32_e32 v122, v122, v86
	v_add_f32_e32 v123, v123, v87
	v_add_f32_e32 v122, v122, v88
	v_add_f32_e32 v123, v123, v89
	v_add_f32_e32 v122, v122, v123
	v_add_f32_e32 v167, v167, v122
	v_add_f32_e32 v124, v90, v91
	v_add_f32_e32 v125, v92, v93
	v_add_f32_e32 v124, v124, v94
	v_add_f32_e32 v125, v125, v95
	v_add_f32_e32 v124, v124, v96
	v_add_f32_e32 v125, v125, v97
	v_add_f32_e32 v124, v124, v125
	v_add_f32_e32 v167, v167, v124
	s_add_i32 m0, s73, 0x7800
	s_nop 0
	global_load_lds_dwordx4 v[134:135], off offset:2048
	s_add_i32 m0, s73, 0x9800
	s_nop 0
	global_load_lds_dwordx4 v[200:201], off offset:2048
	v_lshl_add_u64 v[134:135], v[134:135], 0, s[40:41]
	v_lshl_add_u64 v[200:201], v[200:201], 0, s[40:41]
	s_waitcnt lgkmcnt(8)
	v_mfma_f32_32x32x16_bf16 v[50:65], v[136:139], v[184:187], v[50:65]
	ds_read_b64_tr_b16 v[246:247], v168 offset:53248
	ds_read_b64_tr_b16 v[248:249], v171 offset:53248
	v_exp_f32_e32 v66, v66
	v_exp_f32_e32 v67, v67
	v_exp_f32_e32 v68, v68
	v_mfma_f32_32x32x16_bf16 v[34:49], v[140:143], v[184:187], v[34:49]
	ds_read_b64_tr_b16 v[250:251], v145 offset:53248
	ds_read_b64_tr_b16 v[252:253], v169 offset:53248
	v_exp_f32_e32 v69, v69
	v_exp_f32_e32 v70, v70
	v_exp_f32_e32 v71, v71
	s_waitcnt lgkmcnt(8)
	v_mfma_f32_32x32x16_bf16 v[18:33], v[204:207], v[184:187], v[18:33]
	ds_read_b64_tr_b16 v[136:137], v173 offset:57344
	ds_read_b64_tr_b16 v[138:139], v174 offset:57344
	v_exp_f32_e32 v72, v72
	v_exp_f32_e32 v73, v73
	v_cvt_pk_bf16_f32 v192, v66, v67
	v_mfma_f32_32x32x16_bf16 v[2:17], v[208:211], v[184:187], v[2:17]
	ds_read_b64_tr_b16 v[140:141], v170 offset:57344
	ds_read_b64_tr_b16 v[142:143], v172 offset:57344
	v_cvt_pk_bf16_f32 v193, v68, v69
	v_cvt_pk_bf16_f32 v194, v70, v71
	v_cvt_pk_bf16_f32 v195, v72, v73
	s_waitcnt lgkmcnt(8)
	v_mfma_f32_32x32x16_bf16 v[50:65], v[238:241], v[188:191], v[50:65]
	ds_read_b64_tr_b16 v[204:205], v168 offset:57344
	ds_read_b64_tr_b16 v[206:207], v171 offset:57344
	v_exp_f32_e32 v74, v74
	v_exp_f32_e32 v75, v75
	v_exp_f32_e32 v76, v76
	v_mfma_f32_32x32x16_bf16 v[34:49], v[242:245], v[188:191], v[34:49]
	ds_read_b64_tr_b16 v[208:209], v145 offset:57344
	ds_read_b64_tr_b16 v[210:211], v169 offset:57344
	v_exp_f32_e32 v77, v77
	v_exp_f32_e32 v78, v78
	v_exp_f32_e32 v79, v79
	s_waitcnt lgkmcnt(8)
	v_mfma_f32_32x32x16_bf16 v[18:33], v[246:249], v[188:191], v[18:33]
	ds_read_b64_tr_b16 v[238:239], v173 offset:61440
	ds_read_b64_tr_b16 v[240:241], v174 offset:61440
	v_exp_f32_e32 v80, v80
	v_exp_f32_e32 v81, v81
	v_cvt_pk_bf16_f32 v196, v74, v75
	v_mfma_f32_32x32x16_bf16 v[2:17], v[250:253], v[188:191], v[2:17]
	ds_read_b64_tr_b16 v[242:243], v170 offset:61440
	ds_read_b64_tr_b16 v[244:245], v172 offset:61440
	v_cvt_pk_bf16_f32 v197, v76, v77
	v_cvt_pk_bf16_f32 v198, v78, v79
	v_cvt_pk_bf16_f32 v199, v80, v81
	s_waitcnt lgkmcnt(8)
	v_mfma_f32_32x32x16_bf16 v[50:65], v[136:139], v[192:195], v[50:65]
	ds_read_b64_tr_b16 v[246:247], v168 offset:61440
	ds_read_b64_tr_b16 v[248:249], v171 offset:61440
	v_add_f32_e32 v0, v66, v67
	v_add_f32_e32 v203, v68, v69
	v_add_f32_e32 v0, v0, v70
	v_mfma_f32_32x32x16_bf16 v[34:49], v[140:143], v[192:195], v[34:49]
	ds_read_b64_tr_b16 v[250:251], v145 offset:61440
	ds_read_b64_tr_b16 v[252:253], v169 offset:61440
	v_add_f32_e32 v203, v203, v71
	v_add_f32_e32 v0, v0, v72
	v_add_f32_e32 v203, v203, v73
	s_waitcnt lgkmcnt(8)
	v_mfma_f32_32x32x16_bf16 v[18:33], v[204:207], v[192:195], v[18:33]
	v_add_f32_e32 v0, v0, v203
	v_add_f32_e32 v167, v167, v0
	v_add_f32_e32 v0, v74, v75
	v_mfma_f32_32x32x16_bf16 v[2:17], v[208:211], v[192:195], v[2:17]
	v_add_f32_e32 v203, v76, v77
	v_add_f32_e32 v0, v0, v78
	v_add_f32_e32 v203, v203, v79
	s_waitcnt lgkmcnt(4)
	v_mfma_f32_32x32x16_bf16 v[50:65], v[238:241], v[196:199], v[50:65]
	v_add_f32_e32 v0, v0, v80
	v_add_f32_e32 v203, v203, v81
	v_add_f32_e32 v0, v0, v203
	v_mfma_f32_32x32x16_bf16 v[34:49], v[242:245], v[196:199], v[34:49]
	v_add_f32_e32 v167, v167, v0
	s_waitcnt lgkmcnt(0)
	v_mfma_f32_32x32x16_bf16 v[18:33], v[246:249], v[196:199], v[18:33]
	v_mfma_f32_32x32x16_bf16 v[2:17], v[250:253], v[196:199], v[2:17]
	ds_read_b128 v[136:139], v126 offset:0
	ds_read_b128 v[140:143], v126 offset:8192
	ds_read_b128 v[204:207], v127 offset:0
	ds_read_b128 v[208:211], v127 offset:8192
	ds_read_b128 v[238:241], v128 offset:0
	ds_read_b128 v[242:245], v128 offset:8192
	ds_read_b128 v[246:249], v129 offset:0
	ds_read_b128 v[250:253], v129 offset:8192
	s_waitcnt vmcnt(6)
	s_add_i32 s71, s71, 64
	s_barrier
; #define LAS __attribute__((address_space(3)))
; __device__ __forceinline__ float max3f(float a, float b, float c) { float r; asm("v_max3_f32 %0, %1, %2, %3" : "=v"(r) : "v"(a), "v"(b), "v"(c)); return r; }
; __device__ __forceinline__ void attn_block(LAS unsigned char* lds, const bf16_t* P, bf16_t* mix, int b, int h, int qb, float lam, float outscale, const float* subln) {
;     ...
;         const int kb = 64 * kt;
;         if (kb <= qw0 + 31) {
;             LAS const unsigned char* Kb = lds + ATT_K0 + buf * 16384;
;             LAS const unsigned char* Vb = lds + ATT_V0 + buf * 16384;
;             f32x16 s0, s1;
; #pragma unroll
;             for (int j = 0; j < 16; ++j) { s0[j] = 0.f; s1[j] = 0.f; }
;             bf16x8 ka[4][2];
; #pragma unroll
;             for (int ks = 0; ks < 4; ++ks) { ka[ks][0] = *(const LAS bf16x8*)(Kb + kbase[ks]); ka[ks][1] = *(const LAS bf16x8*)(Kb + kbase[ks] + 8192); }
;             __builtin_amdgcn_sched_barrier(0);
; #pragma unroll
;             for (int ks = 0; ks < 4; ++ks) {
;                 s0 = __builtin_amdgcn_mfma_f32_32x32x16_bf16(ka[ks][0], qf[ks], s0, 0, 0, 0);
;                 s1 = __builtin_amdgcn_mfma_f32_32x32x16_bf16(ka[ks][1], qf[ks], s1, 0, 0, 0);
;             }
;             if (kb + 63 > qw0) {
; #pragma unroll
;                 for (int j = 0; j < 16; ++j) { const int key = kb + crow(j, hi); if (key > qrow) s0[j] = -INFINITY; if (key + 32 > qrow) s1[j] = -INFINITY; }
;             }
;             float mxa = max3f(s0[0], s1[0], s0[1]), mxb = max3f(s1[1], s0[2], s1[2]), mxc = max3f(s0[3], s1[3], s0[4]), mxd = max3f(s1[4], s0[5], s1[5]);
;             mxa = max3f(mxa, s0[6], s1[6]); mxb = max3f(mxb, s0[7], s1[7]); mxc = max3f(mxc, s0[8], s1[8]); mxd = max3f(mxd, s0[9], s1[9]);
;             mxa = max3f(mxa, s0[10], s1[10]); mxb = max3f(mxb, s0[11], s1[11]); mxc = max3f(mxc, s0[12], s1[12]); mxd = max3f(mxd, s0[13], s1[13]);
;             mxa = max3f(mxa, s0[14], s1[14]); mxb = max3f(mxb, s0[15], s1[15]);
;             float mx = max3f(mxa, mxb, max3f(mxc, mxd, mxd));
;             { auto rr = __builtin_amdgcn_permlane32_swap(__builtin_bit_cast(unsigned, mx), __builtin_bit_cast(unsigned, mx), false, false);
;               mx = fmaxf(__builtin_bit_cast(float, rr[0]), __builtin_bit_cast(float, rr[1])); }
;             if (__any(mx > mrun + 8.0f)) {
	s_add_i32 m0, s73, 0x4000
	s_nop 0
	global_load_lds_dwordx4 v[134:135], off
	s_add_i32 m0, s73, 0x6000
	s_nop 0
	global_load_lds_dwordx4 v[200:201], off
	s_waitcnt lgkmcnt(6)
	v_mfma_f32_32x32x16_bf16 v[82:97], v[136:139], v[110:113], v[222:237]
	v_mfma_f32_32x32x16_bf16 v[66:81], v[140:143], v[110:113], v[222:237]
	s_waitcnt lgkmcnt(4)
	v_mfma_f32_32x32x16_bf16 v[82:97], v[204:207], v[106:109], v[82:97]
	v_mfma_f32_32x32x16_bf16 v[66:81], v[208:211], v[106:109], v[66:81]
	s_waitcnt lgkmcnt(2)
	v_mfma_f32_32x32x16_bf16 v[82:97], v[238:241], v[102:105], v[82:97]
	v_mfma_f32_32x32x16_bf16 v[66:81], v[242:245], v[102:105], v[66:81]
	s_waitcnt lgkmcnt(0)
	v_mfma_f32_32x32x16_bf16 v[82:97], v[246:249], v[98:101], v[82:97]
	v_mfma_f32_32x32x16_bf16 v[66:81], v[250:253], v[98:101], v[66:81]
	ds_read_b64_tr_b16 v[136:137], v114 offset:32768
	ds_read_b64_tr_b16 v[138:139], v115 offset:32768
	ds_read_b64_tr_b16 v[140:141], v116 offset:32768
	ds_read_b64_tr_b16 v[142:143], v117 offset:32768
	ds_read_b64_tr_b16 v[204:205], v118 offset:32768
	ds_read_b64_tr_b16 v[206:207], v119 offset:32768
	ds_read_b64_tr_b16 v[208:209], v120 offset:32768
	ds_read_b64_tr_b16 v[210:211], v121 offset:32768
	ds_read_b64_tr_b16 v[238:239], v114 offset:36864
	ds_read_b64_tr_b16 v[240:241], v115 offset:36864
	ds_read_b64_tr_b16 v[242:243], v116 offset:36864
	ds_read_b64_tr_b16 v[244:245], v117 offset:36864
	s_nop 1
	v_max3_f32 v122, v82, v66, v83
	v_max3_f32 v123, v67, v84, v68
	v_max3_f32 v124, v85, v69, v86
	v_max3_f32 v125, v70, v87, v71
	v_max3_f32 v122, v122, v88, v72
	v_max3_f32 v123, v123, v89, v73
	v_max3_f32 v124, v124, v90, v74
	v_max3_f32 v125, v125, v91, v75
	v_max3_f32 v122, v122, v92, v76
	v_max3_f32 v123, v123, v93, v77
	v_max3_f32 v124, v124, v94, v78
	v_max3_f32 v125, v125, v95, v79
	v_max3_f32 v122, v122, v96, v80
	v_max3_f32 v123, v123, v97, v81
	v_max3_f32 v122, v122, v123, v124
	v_max_f32_e32 v122, v122, v125
	v_mov_b32_e32 v203, v122
	s_nop 1
	v_permlane32_swap_b32_e32 v122, v203
	s_nop 1
	v_max_f32_e32 v122, v122, v203
	s_mov_b32 s70, 0
	v_cmp_lt_f32_e32 vcc, 0x41000000, v122
	s_cmp_eq_u32 s71, 0
	s_cbranch_scc1 .Lat1_u2_first
	s_cbranch_vccz .Lat1_u2_norescale
	s_branch .Lat1_u2_rescale

; #define LAS __attribute__((address_space(3)))
; __device__ __forceinline__ unsigned pk2(float lo, float hi) { f32x2 v = {lo, hi}; bf16x2_t b = __builtin_convertvector(v, bf16x2_t); return __builtin_bit_cast(unsigned, b); }
; __device__ __forceinline__ s16x4 vtr(LAS const unsigned char* p) { return __builtin_bit_cast(s16x4, __builtin_amdgcn_ds_read_tr16_b64_v4i16((LAS v4i16_t*)p)); }
; __device__ __forceinline__ bf16x8 cat8(s16x4 a, s16x4 b) { return (bf16x8){a[0], a[1], a[2], a[3], b[0], b[1], b[2], b[3]}; }
; __device__ __forceinline__ void attn_block(LAS unsigned char* lds, const bf16_t* P, bf16_t* mix, int b, int h, int qb, float lam, float outscale, const float* subln) {
;     ...
;             for (int ks = 0; ks < 4; ++ks) { ka[ks][0] = *(const LAS bf16x8*)(Kb + kbase[ks]); ka[ks][1] = *(const LAS bf16x8*)(Kb + kbase[ks] + 8192); }
;     ...
; #pragma unroll
;             for (int j = 0; j < 16; ++j) { s0[j] = __builtin_amdgcn_exp2f(s0[j] - mrun); s1[j] = __builtin_amdgcn_exp2f(s1[j] - mrun); }
;             float ps0 = 0.f, ps1 = 0.f, ps2 = 0.f, ps3 = 0.f;
; #pragma unroll
;             for (int j = 0; j < 16; j += 2) { ps0 += s0[j]; ps1 += s1[j]; ps2 += s0[j + 1]; ps3 += s1[j + 1]; }
;             lrun += (ps0 + ps1) + (ps2 + ps3);
;             bf16x8 pb[4];
; #pragma unroll
;             for (int s2 = 0; s2 < 2; ++s2) {
;                 u32x4 w0, w1;
;                 w0.x = pk2(s0[8 * s2 + 0], s0[8 * s2 + 1]); w0.y = pk2(s0[8 * s2 + 2], s0[8 * s2 + 3]); w0.z = pk2(s0[8 * s2 + 4], s0[8 * s2 + 5]); w0.w = pk2(s0[8 * s2 + 6], s0[8 * s2 + 7]);
;                 w1.x = pk2(s1[8 * s2 + 0], s1[8 * s2 + 1]); w1.y = pk2(s1[8 * s2 + 2], s1[8 * s2 + 3]); w1.z = pk2(s1[8 * s2 + 4], s1[8 * s2 + 5]); w1.w = pk2(s1[8 * s2 + 6], s1[8 * s2 + 7]);
;                 pb[s2] = __builtin_bit_cast(bf16x8, w0); pb[2 + s2] = __builtin_bit_cast(bf16x8, w1);
;             }
; #pragma unroll
;             for (int s = 0; s < 4; ++s) {
; #pragma unroll
;                 for (int c = 0; c < 4; ++c) {
;                     const s16x4 v0 = vtr(Vb + vbase[c][0] + 4096 * s);
;                     const s16x4 v1 = vtr(Vb + vbase[c][1] + 4096 * s);
;                     o[c] = __builtin_amdgcn_mfma_f32_32x32x16_bf16(cat8(v0, v1), pb[s], o[c], 0, 0, 0);
;                 }
;             }
.Lat1_u2_norescale:
	v_exp_f32_e32 v82, v82
	v_exp_f32_e32 v83, v83
	v_exp_f32_e32 v84, v84
	v_exp_f32_e32 v85, v85
	v_exp_f32_e32 v86, v86
	v_exp_f32_e32 v87, v87
	v_exp_f32_e32 v88, v88
	v_exp_f32_e32 v89, v89
	v_exp_f32_e32 v90, v90
	v_exp_f32_e32 v91, v91
	v_exp_f32_e32 v92, v92
	v_exp_f32_e32 v93, v93
	v_exp_f32_e32 v94, v94
	v_exp_f32_e32 v95, v95
	v_exp_f32_e32 v96, v96
	v_exp_f32_e32 v97, v97
	v_cvt_pk_bf16_f32 v184, v82, v83
	v_cvt_pk_bf16_f32 v185, v84, v85
	v_cvt_pk_bf16_f32 v186, v86, v87
	v_cvt_pk_bf16_f32 v187, v88, v89
	v_cvt_pk_bf16_f32 v188, v90, v91
	v_cvt_pk_bf16_f32 v189, v92, v93
	v_cvt_pk_bf16_f32 v190, v94, v95
	v_cvt_pk_bf16_f32 v191, v96, v97
	v_add_f32_e32 v122, v82, v83
	v_add_f32_e32 v123, v84, v85
	v_add_f32_e32 v122, v122, v86
	v_add_f32_e32 v123, v123, v87
	v_add_f32_e32 v122, v122, v88
	v_add_f32_e32 v123, v123, v89
	v_add_f32_e32 v122, v122, v123
	v_add_f32_e32 v167, v167, v122
	v_add_f32_e32 v124, v90, v91
	v_add_f32_e32 v125, v92, v93
	v_add_f32_e32 v124, v124, v94
	v_add_f32_e32 v125, v125, v95
	v_add_f32_e32 v124, v124, v96
	v_add_f32_e32 v125, v125, v97
	v_add_f32_e32 v124, v124, v125
	v_add_f32_e32 v167, v167, v124
	s_add_i32 m0, s73, 0xb800
	s_nop 0
	global_load_lds_dwordx4 v[134:135], off offset:2048
	s_add_i32 m0, s73, 0xd800
	s_nop 0
	global_load_lds_dwordx4 v[200:201], off offset:2048
	v_lshl_add_u64 v[134:135], v[134:135], 0, s[40:41]
	v_lshl_add_u64 v[200:201], v[200:201], 0, s[40:41]
	s_waitcnt lgkmcnt(8)
	v_mfma_f32_32x32x16_bf16 v[50:65], v[136:139], v[184:187], v[50:65]
	ds_read_b64_tr_b16 v[246:247], v118 offset:36864
	ds_read_b64_tr_b16 v[248:249], v119 offset:36864
	v_exp_f32_e32 v66, v66
	v_exp_f32_e32 v67, v67
	v_exp_f32_e32 v68, v68
	v_mfma_f32_32x32x16_bf16 v[34:49], v[140:143], v[184:187], v[34:49]
	ds_read_b64_tr_b16 v[250:251], v120 offset:36864
	ds_read_b64_tr_b16 v[252:253], v121 offset:36864
	v_exp_f32_e32 v69, v69
	v_exp_f32_e32 v70, v70
	v_exp_f32_e32 v71, v71
	s_waitcnt lgkmcnt(8)
	v_mfma_f32_32x32x16_bf16 v[18:33], v[204:207], v[184:187], v[18:33]
	ds_read_b64_tr_b16 v[136:137], v114 offset:40960
	ds_read_b64_tr_b16 v[138:139], v115 offset:40960
	v_exp_f32_e32 v72, v72
	v_exp_f32_e32 v73, v73
	v_cvt_pk_bf16_f32 v192, v66, v67
	v_mfma_f32_32x32x16_bf16 v[2:17], v[208:211], v[184:187], v[2:17]
	ds_read_b64_tr_b16 v[140:141], v116 offset:40960
	ds_read_b64_tr_b16 v[142:143], v117 offset:40960
	v_cvt_pk_bf16_f32 v193, v68, v69
	v_cvt_pk_bf16_f32 v194, v70, v71
	v_cvt_pk_bf16_f32 v195, v72, v73
	s_waitcnt lgkmcnt(8)
	v_mfma_f32_32x32x16_bf16 v[50:65], v[238:241], v[188:191], v[50:65]
	ds_read_b64_tr_b16 v[204:205], v118 offset:40960
	ds_read_b64_tr_b16 v[206:207], v119 offset:40960
	v_exp_f32_e32 v74, v74
	v_exp_f32_e32 v75, v75
	v_exp_f32_e32 v76, v76
	v_mfma_f32_32x32x16_bf16 v[34:49], v[242:245], v[188:191], v[34:49]
	ds_read_b64_tr_b16 v[208:209], v120 offset:40960
	ds_read_b64_tr_b16 v[210:211], v121 offset:40960
	v_exp_f32_e32 v77, v77
	v_exp_f32_e32 v78, v78
	v_exp_f32_e32 v79, v79
	s_waitcnt lgkmcnt(8)
	v_mfma_f32_32x32x16_bf16 v[18:33], v[246:249], v[188:191], v[18:33]
	ds_read_b64_tr_b16 v[238:239], v114 offset:45056
	ds_read_b64_tr_b16 v[240:241], v115 offset:45056
	v_exp_f32_e32 v80, v80
	v_exp_f32_e32 v81, v81
	v_cvt_pk_bf16_f32 v196, v74, v75
	v_mfma_f32_32x32x16_bf16 v[2:17], v[250:253], v[188:191], v[2:17]
	ds_read_b64_tr_b16 v[242:243], v116 offset:45056
	ds_read_b64_tr_b16 v[244:245], v117 offset:45056
	v_cvt_pk_bf16_f32 v197, v76, v77
	v_cvt_pk_bf16_f32 v198, v78, v79
	v_cvt_pk_bf16_f32 v199, v80, v81
	s_waitcnt lgkmcnt(8)
	v_mfma_f32_32x32x16_bf16 v[50:65], v[136:139], v[192:195], v[50:65]
	ds_read_b64_tr_b16 v[246:247], v118 offset:45056
	ds_read_b64_tr_b16 v[248:249], v119 offset:45056
	v_add_f32_e32 v0, v66, v67
	v_add_f32_e32 v203, v68, v69
	v_add_f32_e32 v0, v0, v70
	v_mfma_f32_32x32x16_bf16 v[34:49], v[140:143], v[192:195], v[34:49]
	ds_read_b64_tr_b16 v[250:251], v120 offset:45056
	ds_read_b64_tr_b16 v[252:253], v121 offset:45056
	v_add_f32_e32 v203, v203, v71
	v_add_f32_e32 v0, v0, v72
	v_add_f32_e32 v203, v203, v73
	s_waitcnt lgkmcnt(8)
	v_mfma_f32_32x32x16_bf16 v[18:33], v[204:207], v[192:195], v[18:33]
	v_add_f32_e32 v0, v0, v203
	v_add_f32_e32 v167, v167, v0
	v_add_f32_e32 v0, v74, v75
	v_mfma_f32_32x32x16_bf16 v[2:17], v[208:211], v[192:195], v[2:17]
	v_add_f32_e32 v203, v76, v77
	v_add_f32_e32 v0, v0, v78
	v_add_f32_e32 v203, v203, v79
	s_waitcnt lgkmcnt(4)
	v_mfma_f32_32x32x16_bf16 v[50:65], v[238:241], v[196:199], v[50:65]
	v_add_f32_e32 v0, v0, v80
	v_add_f32_e32 v203, v203, v81
	v_add_f32_e32 v0, v0, v203
	v_mfma_f32_32x32x16_bf16 v[34:49], v[242:245], v[196:199], v[34:49]
	v_add_f32_e32 v167, v167, v0
	s_waitcnt lgkmcnt(0)
	v_mfma_f32_32x32x16_bf16 v[18:33], v[246:249], v[196:199], v[18:33]
	v_mfma_f32_32x32x16_bf16 v[2:17], v[250:253], v[196:199], v[2:17]
	ds_read_b128 v[136:139], v126 offset:16384
	ds_read_b128 v[140:143], v126 offset:24576
	ds_read_b128 v[204:207], v127 offset:16384
	ds_read_b128 v[208:211], v127 offset:24576
	ds_read_b128 v[238:241], v128 offset:16384
	ds_read_b128 v[242:245], v128 offset:24576
	ds_read_b128 v[246:249], v129 offset:16384
	ds_read_b128 v[250:253], v129 offset:24576
	s_waitcnt vmcnt(6)
	s_add_i32 s71, s71, 64
	s_barrier
; #define LAS __attribute__((address_space(3)))
; __device__ __forceinline__ float max3f(float a, float b, float c) { float r; asm("v_max3_f32 %0, %1, %2, %3" : "=v"(r) : "v"(a), "v"(b), "v"(c)); return r; }
; __device__ __forceinline__ void attn_block(LAS unsigned char* lds, const bf16_t* P, bf16_t* mix, int b, int h, int qb, float lam, float outscale, const float* subln) {
;     ...
;         const int kb = 64 * kt;
;         if (kb <= qw0 + 31) {
;             LAS const unsigned char* Kb = lds + ATT_K0 + buf * 16384;
;             LAS const unsigned char* Vb = lds + ATT_V0 + buf * 16384;
;             f32x16 s0, s1;
; #pragma unroll
;             for (int j = 0; j < 16; ++j) { s0[j] = 0.f; s1[j] = 0.f; }
;             bf16x8 ka[4][2];
; #pragma unroll
;             for (int ks = 0; ks < 4; ++ks) { ka[ks][0] = *(const LAS bf16x8*)(Kb + kbase[ks]); ka[ks][1] = *(const LAS bf16x8*)(Kb + kbase[ks] + 8192); }
;             __builtin_amdgcn_sched_barrier(0);
; #pragma unroll
;             for (int ks = 0; ks < 4; ++ks) {
;                 s0 = __builtin_amdgcn_mfma_f32_32x32x16_bf16(ka[ks][0], qf[ks], s0, 0, 0, 0);
;                 s1 = __builtin_amdgcn_mfma_f32_32x32x16_bf16(ka[ks][1], qf[ks], s1, 0, 0, 0);
;             }
;             if (kb + 63 > qw0) {
; #pragma unroll
;                 for (int j = 0; j < 16; ++j) { const int key = kb + crow(j, hi); if (key > qrow) s0[j] = -INFINITY; if (key + 32 > qrow) s1[j] = -INFINITY; }
;             }
;             float mxa = max3f(s0[0], s1[0], s0[1]), mxb = max3f(s1[1], s0[2], s1[2]), mxc = max3f(s0[3], s1[3], s0[4]), mxd = max3f(s1[4], s0[5], s1[5]);
;             mxa = max3f(mxa, s0[6], s1[6]); mxb = max3f(mxb, s0[7], s1[7]); mxc = max3f(mxc, s0[8], s1[8]); mxd = max3f(mxd, s0[9], s1[9]);
;             mxa = max3f(mxa, s0[10], s1[10]); mxb = max3f(mxb, s0[11], s1[11]); mxc = max3f(mxc, s0[12], s1[12]); mxd = max3f(mxd, s0[13], s1[13]);
;             mxa = max3f(mxa, s0[14], s1[14]); mxb = max3f(mxb, s0[15], s1[15]);
;             float mx = max3f(mxa, mxb, max3f(mxc, mxd, mxd));
;             { auto rr = __builtin_amdgcn_permlane32_swap(__builtin_bit_cast(unsigned, mx), __builtin_bit_cast(unsigned, mx), false, false);
;               mx = fmaxf(__builtin_bit_cast(float, rr[0]), __builtin_bit_cast(float, rr[1])); }
;             if (__any(mx > mrun + 8.0f)) {
	s_add_i32 m0, s73, 0x10000
	s_nop 0
	global_load_lds_dwordx4 v[134:135], off
	s_add_i32 m0, s73, 0x12000
	s_nop 0
	global_load_lds_dwordx4 v[200:201], off
	s_waitcnt lgkmcnt(6)
	v_mfma_f32_32x32x16_bf16 v[82:97], v[136:139], v[110:113], v[222:237]
	v_mfma_f32_32x32x16_bf16 v[66:81], v[140:143], v[110:113], v[222:237]
	s_waitcnt lgkmcnt(4)
	v_mfma_f32_32x32x16_bf16 v[82:97], v[204:207], v[106:109], v[82:97]
	v_mfma_f32_32x32x16_bf16 v[66:81], v[208:211], v[106:109], v[66:81]
	s_waitcnt lgkmcnt(2)
	v_mfma_f32_32x32x16_bf16 v[82:97], v[238:241], v[102:105], v[82:97]
	v_mfma_f32_32x32x16_bf16 v[66:81], v[242:245], v[102:105], v[66:81]
	s_waitcnt lgkmcnt(0)
	v_mfma_f32_32x32x16_bf16 v[82:97], v[246:249], v[98:101], v[82:97]
	v_mfma_f32_32x32x16_bf16 v[66:81], v[250:253], v[98:101], v[66:81]
	ds_read_b64_tr_b16 v[136:137], v114 offset:49152
	ds_read_b64_tr_b16 v[138:139], v115 offset:49152
	ds_read_b64_tr_b16 v[140:141], v116 offset:49152
	ds_read_b64_tr_b16 v[142:143], v117 offset:49152
	ds_read_b64_tr_b16 v[204:205], v118 offset:49152
	ds_read_b64_tr_b16 v[206:207], v119 offset:49152
	ds_read_b64_tr_b16 v[208:209], v120 offset:49152
	ds_read_b64_tr_b16 v[210:211], v121 offset:49152
	ds_read_b64_tr_b16 v[238:239], v114 offset:53248
	ds_read_b64_tr_b16 v[240:241], v115 offset:53248
	ds_read_b64_tr_b16 v[242:243], v116 offset:53248
	ds_read_b64_tr_b16 v[244:245], v117 offset:53248
	s_nop 1
	v_max3_f32 v122, v82, v66, v83
	v_max3_f32 v123, v67, v84, v68
	v_max3_f32 v124, v85, v69, v86
	v_max3_f32 v125, v70, v87, v71
	v_max3_f32 v122, v122, v88, v72
	v_max3_f32 v123, v123, v89, v73
	v_max3_f32 v124, v124, v90, v74
	v_max3_f32 v125, v125, v91, v75
	v_max3_f32 v122, v122, v92, v76
	v_max3_f32 v123, v123, v93, v77
	v_max3_f32 v124, v124, v94, v78
	v_max3_f32 v125, v125, v95, v79
	v_max3_f32 v122, v122, v96, v80
	v_max3_f32 v123, v123, v97, v81
	v_max3_f32 v122, v122, v123, v124
	v_max_f32_e32 v122, v122, v125
	v_mov_b32_e32 v203, v122
	s_nop 1
	v_permlane32_swap_b32_e32 v122, v203
	s_nop 1
	v_max_f32_e32 v122, v122, v203
	s_mov_b32 s70, 0
	v_cmp_lt_f32_e32 vcc, 0x41000000, v122
	s_cmp_eq_u32 s71, 0
	s_cbranch_scc1 .Lat1_u3_first
	s_cbranch_vccz .Lat1_u3_norescale
	s_branch .Lat1_u3_rescale

; #define LAS __attribute__((address_space(3)))
; __device__ __forceinline__ void attn_block(LAS unsigned char* lds, const bf16_t* P, bf16_t* mix, int b, int h, int qb, float lam, float outscale, const float* subln) {
;     ...
;     for (int kt = 0; kt < ntiles; ++kt) {
;         __syncthreads();
;         const int buf = kt & 1;
;         if (kt + 1 < ntiles) {
;             const size_t ro = (size_t)(64 * (kt + 1)) * INC;
;             kr0 = *(const u32x4*)(kg + ro + (size_t)srow * INC); kr1 = *(const u32x4*)(kg + ro + (size_t)(srow + 32) * INC);
;             vr0 = *(const u32x4*)(vg + ro + (size_t)srow * INC); vr1 = *(const u32x4*)(vg + ro + (size_t)(srow + 32) * INC);
;         }
;         const int kb = 64 * kt;
;         if (kb <= qw0 + 31) {
;             LAS const unsigned char* Kb = lds + ATT_K0 + buf * 16384;
;             LAS const unsigned char* Vb = lds + ATT_V0 + buf * 16384;
;             f32x16 s0, s1;
; #pragma unroll
;             for (int j = 0; j < 16; ++j) { s0[j] = 0.f; s1[j] = 0.f; }
;             bf16x8 ka[4][2];
; #pragma unroll
;             for (int ks = 0; ks < 4; ++ks) { ka[ks][0] = *(const LAS bf16x8*)(Kb + kbase[ks]); ka[ks][1] = *(const LAS bf16x8*)(Kb + kbase[ks] + 8192); }
;             __builtin_amdgcn_sched_barrier(0);
; #pragma unroll
;             for (int ks = 0; ks < 4; ++ks) {
;                 s0 = __builtin_amdgcn_mfma_f32_32x32x16_bf16(ka[ks][0], qf[ks], s0, 0, 0, 0);
;                 s1 = __builtin_amdgcn_mfma_f32_32x32x16_bf16(ka[ks][1], qf[ks], s1, 0, 0, 0);
;             }
;             if (kb + 63 > qw0) {
; #pragma unroll
;                 for (int j = 0; j < 16; ++j) { const int key = kb + crow(j, hi); if (key > qrow) s0[j] = -INFINITY; if (key + 32 > qrow) s1[j] = -INFINITY; }
;             }
;             float mxa = max3f(s0[0], s1[0], s0[1]), mxb = max3f(s1[1], s0[2], s1[2]), mxc = max3f(s0[3], s1[3], s0[4]), mxd = max3f(s1[4], s0[5], s1[5]);
;             mxa = max3f(mxa, s0[6], s1[6]); mxb = max3f(mxb, s0[7], s1[7]); mxc = max3f(mxc, s0[8], s1[8]); mxd = max3f(mxd, s0[9], s1[9]);
;             mxa = max3f(mxa, s0[10], s1[10]); mxb = max3f(mxb, s0[11], s1[11]); mxc = max3f(mxc, s0[12], s1[12]); mxd = max3f(mxd, s0[13], s1[13]);
;             mxa = max3f(mxa, s0[14], s1[14]); mxb = max3f(mxb, s0[15], s1[15]);
;             float mx = max3f(mxa, mxb, max3f(mxc, mxd, mxd));
.Lat2_U_top:
	s_add_i32 m0, s62, 0x14000
	s_nop 0
	global_load_lds_dwordx4 v[134:135], off
	s_add_i32 m0, s62, 0x16000
	s_nop 0
	global_load_lds_dwordx4 v[200:201], off
	s_waitcnt lgkmcnt(6)
	v_mfma_f32_32x32x16_bf16 v[82:97], v[136:139], v[110:113], v[222:237]
	v_mfma_f32_32x32x16_bf16 v[66:81], v[140:143], v[110:113], v[222:237]
	s_waitcnt lgkmcnt(4)
	v_mfma_f32_32x32x16_bf16 v[82:97], v[204:207], v[106:109], v[82:97]
	v_mfma_f32_32x32x16_bf16 v[66:81], v[208:211], v[106:109], v[66:81]
	s_waitcnt lgkmcnt(2)
	v_mfma_f32_32x32x16_bf16 v[82:97], v[238:241], v[102:105], v[82:97]
	v_mfma_f32_32x32x16_bf16 v[66:81], v[242:245], v[102:105], v[66:81]
	s_waitcnt lgkmcnt(0)
	v_mfma_f32_32x32x16_bf16 v[82:97], v[246:249], v[98:101], v[82:97]
	v_mfma_f32_32x32x16_bf16 v[66:81], v[250:253], v[98:101], v[66:81]
	ds_read_b64_tr_b16 v[136:137], v168 offset:32768
	ds_read_b64_tr_b16 v[138:139], v175 offset:32768
	ds_read_b64_tr_b16 v[140:141], v172 offset:32768
	ds_read_b64_tr_b16 v[142:143], v174 offset:32768
	ds_read_b64_tr_b16 v[204:205], v170 offset:32768
	ds_read_b64_tr_b16 v[206:207], v173 offset:32768
	ds_read_b64_tr_b16 v[208:209], v169 offset:32768
	ds_read_b64_tr_b16 v[210:211], v171 offset:32768
	ds_read_b64_tr_b16 v[238:239], v168 offset:36864
	ds_read_b64_tr_b16 v[240:241], v175 offset:36864
	ds_read_b64_tr_b16 v[242:243], v172 offset:36864
	ds_read_b64_tr_b16 v[244:245], v174 offset:36864
	s_nop 1
	v_max3_f32 v122, v82, v66, v83
	v_max3_f32 v123, v67, v84, v68
	v_max3_f32 v124, v85, v69, v86
	v_max3_f32 v125, v70, v87, v71
	v_max3_f32 v122, v122, v88, v72
	v_max3_f32 v123, v123, v89, v73
	v_max3_f32 v124, v124, v90, v74
	v_max3_f32 v125, v125, v91, v75
	v_max3_f32 v122, v122, v92, v76
	v_max3_f32 v123, v123, v93, v77
	v_max3_f32 v124, v124, v94, v78
	v_max3_f32 v125, v125, v95, v79
	v_max3_f32 v122, v122, v96, v80
	v_max3_f32 v123, v123, v97, v81
	v_max3_f32 v122, v122, v123, v124
	v_max_f32_e32 v122, v122, v125
	v_mov_b32_e32 v203, v122
	s_nop 1
	v_permlane32_swap_b32_e32 v122, v203
	s_nop 1
	v_max_f32_e32 v122, v122, v203
	s_mov_b32 s39, 0
	v_cmp_lt_f32_e32 vcc, 0x41000000, v122
	s_cmp_eq_u32 s50, 0
	s_cbranch_scc1 .Lat2_u0_first
	s_cbranch_vccz .Lat2_u0_norescale
	s_branch .Lat2_u0_rescale

; #define LAS __attribute__((address_space(3)))
; __device__ __forceinline__ unsigned pk2(float lo, float hi) { f32x2 v = {lo, hi}; bf16x2_t b = __builtin_convertvector(v, bf16x2_t); return __builtin_bit_cast(unsigned, b); }
; __device__ __forceinline__ s16x4 vtr(LAS const unsigned char* p) { return __builtin_bit_cast(s16x4, __builtin_amdgcn_ds_read_tr16_b64_v4i16((LAS v4i16_t*)p)); }
; __device__ __forceinline__ bf16x8 cat8(s16x4 a, s16x4 b) { return (bf16x8){a[0], a[1], a[2], a[3], b[0], b[1], b[2], b[3]}; }
; __device__ __forceinline__ void attn_block(LAS unsigned char* lds, const bf16_t* P, bf16_t* mix, int b, int h, int qb, float lam, float outscale, const float* subln) {
;     ...
;             for (int ks = 0; ks < 4; ++ks) { ka[ks][0] = *(const LAS bf16x8*)(Kb + kbase[ks]); ka[ks][1] = *(const LAS bf16x8*)(Kb + kbase[ks] + 8192); }
;     ...
; #pragma unroll
;             for (int j = 0; j < 16; ++j) { s0[j] = __builtin_amdgcn_exp2f(s0[j] - mrun); s1[j] = __builtin_amdgcn_exp2f(s1[j] - mrun); }
;             float ps0 = 0.f, ps1 = 0.f, ps2 = 0.f, ps3 = 0.f;
; #pragma unroll
;             for (int j = 0; j < 16; j += 2) { ps0 += s0[j]; ps1 += s1[j]; ps2 += s0[j + 1]; ps3 += s1[j + 1]; }
;             lrun += (ps0 + ps1) + (ps2 + ps3);
;             bf16x8 pb[4];
; #pragma unroll
;             for (int s2 = 0; s2 < 2; ++s2) {
;                 u32x4 w0, w1;
;                 w0.x = pk2(s0[8 * s2 + 0], s0[8 * s2 + 1]); w0.y = pk2(s0[8 * s2 + 2], s0[8 * s2 + 3]); w0.z = pk2(s0[8 * s2 + 4], s0[8 * s2 + 5]); w0.w = pk2(s0[8 * s2 + 6], s0[8 * s2 + 7]);
;                 w1.x = pk2(s1[8 * s2 + 0], s1[8 * s2 + 1]); w1.y = pk2(s1[8 * s2 + 2], s1[8 * s2 + 3]); w1.z = pk2(s1[8 * s2 + 4], s1[8 * s2 + 5]); w1.w = pk2(s1[8 * s2 + 6], s1[8 * s2 + 7]);
;                 pb[s2] = __builtin_bit_cast(bf16x8, w0); pb[2 + s2] = __builtin_bit_cast(bf16x8, w1);
;             }
; #pragma unroll
;             for (int s = 0; s < 4; ++s) {
; #pragma unroll
;                 for (int c = 0; c < 4; ++c) {
;                     const s16x4 v0 = vtr(Vb + vbase[c][0] + 4096 * s);
;                     const s16x4 v1 = vtr(Vb + vbase[c][1] + 4096 * s);
;                     o[c] = __builtin_amdgcn_mfma_f32_32x32x16_bf16(cat8(v0, v1), pb[s], o[c], 0, 0, 0);
;                 }
;             }
.Lat2_u0_norescale:
	v_exp_f32_e32 v82, v82
	v_exp_f32_e32 v83, v83
	v_exp_f32_e32 v84, v84
	v_exp_f32_e32 v85, v85
	v_exp_f32_e32 v86, v86
	v_exp_f32_e32 v87, v87
	v_exp_f32_e32 v88, v88
	v_exp_f32_e32 v89, v89
	v_exp_f32_e32 v90, v90
	v_exp_f32_e32 v91, v91
	v_exp_f32_e32 v92, v92
	v_exp_f32_e32 v93, v93
	v_exp_f32_e32 v94, v94
	v_exp_f32_e32 v95, v95
	v_exp_f32_e32 v96, v96
	v_exp_f32_e32 v97, v97
	v_cvt_pk_bf16_f32 v184, v82, v83
	v_cvt_pk_bf16_f32 v185, v84, v85
	v_cvt_pk_bf16_f32 v186, v86, v87
	v_cvt_pk_bf16_f32 v187, v88, v89
	v_cvt_pk_bf16_f32 v188, v90, v91
	v_cvt_pk_bf16_f32 v189, v92, v93
	v_cvt_pk_bf16_f32 v190, v94, v95
	v_cvt_pk_bf16_f32 v191, v96, v97
	v_add_f32_e32 v122, v82, v83
	v_add_f32_e32 v123, v84, v85
	v_add_f32_e32 v122, v122, v86
	v_add_f32_e32 v123, v123, v87
	v_add_f32_e32 v122, v122, v88
	v_add_f32_e32 v123, v123, v89
	v_add_f32_e32 v122, v122, v123
	v_add_f32_e32 v167, v167, v122
	v_add_f32_e32 v124, v90, v91
	v_add_f32_e32 v125, v92, v93
	v_add_f32_e32 v124, v124, v94
	v_add_f32_e32 v125, v125, v95
	v_add_f32_e32 v124, v124, v96
	v_add_f32_e32 v125, v125, v97
	v_add_f32_e32 v124, v124, v125
	v_add_f32_e32 v167, v167, v124
	s_add_i32 m0, s62, 0x1b800
	s_nop 0
	global_load_lds_dwordx4 v[134:135], off offset:2048
	s_add_i32 m0, s62, 0x1d800
	s_nop 0
	global_load_lds_dwordx4 v[200:201], off offset:2048
	v_lshl_add_u64 v[134:135], v[134:135], 0, s[40:41]
	v_lshl_add_u64 v[200:201], v[200:201], 0, s[40:41]
	s_waitcnt lgkmcnt(8)
	v_mfma_f32_32x32x16_bf16 v[50:65], v[136:139], v[184:187], v[50:65]
	ds_read_b64_tr_b16 v[246:247], v170 offset:36864
	ds_read_b64_tr_b16 v[248:249], v173 offset:36864
	v_exp_f32_e32 v66, v66
	v_exp_f32_e32 v67, v67
	v_exp_f32_e32 v68, v68
	v_mfma_f32_32x32x16_bf16 v[34:49], v[140:143], v[184:187], v[34:49]
	ds_read_b64_tr_b16 v[250:251], v169 offset:36864
	ds_read_b64_tr_b16 v[252:253], v171 offset:36864
	v_exp_f32_e32 v69, v69
	v_exp_f32_e32 v70, v70
	v_exp_f32_e32 v71, v71
	s_waitcnt lgkmcnt(8)
	v_mfma_f32_32x32x16_bf16 v[18:33], v[204:207], v[184:187], v[18:33]
	ds_read_b64_tr_b16 v[136:137], v168 offset:40960
	ds_read_b64_tr_b16 v[138:139], v175 offset:40960
	v_exp_f32_e32 v72, v72
	v_exp_f32_e32 v73, v73
	v_cvt_pk_bf16_f32 v192, v66, v67
	v_mfma_f32_32x32x16_bf16 v[2:17], v[208:211], v[184:187], v[2:17]
	ds_read_b64_tr_b16 v[140:141], v172 offset:40960
	ds_read_b64_tr_b16 v[142:143], v174 offset:40960
	v_cvt_pk_bf16_f32 v193, v68, v69
	v_cvt_pk_bf16_f32 v194, v70, v71
	v_cvt_pk_bf16_f32 v195, v72, v73
	s_waitcnt lgkmcnt(8)
	v_mfma_f32_32x32x16_bf16 v[50:65], v[238:241], v[188:191], v[50:65]
	ds_read_b64_tr_b16 v[204:205], v170 offset:40960
	ds_read_b64_tr_b16 v[206:207], v173 offset:40960
	v_exp_f32_e32 v74, v74
	v_exp_f32_e32 v75, v75
	v_exp_f32_e32 v76, v76
	v_mfma_f32_32x32x16_bf16 v[34:49], v[242:245], v[188:191], v[34:49]
	ds_read_b64_tr_b16 v[208:209], v169 offset:40960
	ds_read_b64_tr_b16 v[210:211], v171 offset:40960
	v_exp_f32_e32 v77, v77
	v_exp_f32_e32 v78, v78
	v_exp_f32_e32 v79, v79
	s_waitcnt lgkmcnt(8)
	v_mfma_f32_32x32x16_bf16 v[18:33], v[246:249], v[188:191], v[18:33]
	ds_read_b64_tr_b16 v[238:239], v168 offset:45056
	ds_read_b64_tr_b16 v[240:241], v175 offset:45056
	v_exp_f32_e32 v80, v80
	v_exp_f32_e32 v81, v81
	v_cvt_pk_bf16_f32 v196, v74, v75
	v_mfma_f32_32x32x16_bf16 v[2:17], v[250:253], v[188:191], v[2:17]
	ds_read_b64_tr_b16 v[242:243], v172 offset:45056
	ds_read_b64_tr_b16 v[244:245], v174 offset:45056
	v_cvt_pk_bf16_f32 v197, v76, v77
	v_cvt_pk_bf16_f32 v198, v78, v79
	v_cvt_pk_bf16_f32 v199, v80, v81
	s_waitcnt lgkmcnt(8)
	v_mfma_f32_32x32x16_bf16 v[50:65], v[136:139], v[192:195], v[50:65]
	ds_read_b64_tr_b16 v[246:247], v170 offset:45056
	ds_read_b64_tr_b16 v[248:249], v173 offset:45056
	v_add_f32_e32 v0, v66, v67
	v_add_f32_e32 v203, v68, v69
	v_add_f32_e32 v0, v0, v70
	v_mfma_f32_32x32x16_bf16 v[34:49], v[140:143], v[192:195], v[34:49]
	ds_read_b64_tr_b16 v[250:251], v169 offset:45056
	ds_read_b64_tr_b16 v[252:253], v171 offset:45056
	v_add_f32_e32 v203, v203, v71
	v_add_f32_e32 v0, v0, v72
	v_add_f32_e32 v203, v203, v73
	s_waitcnt lgkmcnt(8)
	v_mfma_f32_32x32x16_bf16 v[18:33], v[204:207], v[192:195], v[18:33]
	v_add_f32_e32 v0, v0, v203
	v_add_f32_e32 v167, v167, v0
	v_add_f32_e32 v0, v74, v75
	v_mfma_f32_32x32x16_bf16 v[2:17], v[208:211], v[192:195], v[2:17]
	v_add_f32_e32 v203, v76, v77
	v_add_f32_e32 v0, v0, v78
	v_add_f32_e32 v203, v203, v79
	s_waitcnt lgkmcnt(4)
	v_mfma_f32_32x32x16_bf16 v[50:65], v[238:241], v[196:199], v[50:65]
	v_add_f32_e32 v0, v0, v80
	v_add_f32_e32 v203, v203, v81
	v_add_f32_e32 v0, v0, v203
	v_mfma_f32_32x32x16_bf16 v[34:49], v[242:245], v[196:199], v[34:49]
	v_add_f32_e32 v167, v167, v0
	s_waitcnt lgkmcnt(0)
	v_mfma_f32_32x32x16_bf16 v[18:33], v[246:249], v[196:199], v[18:33]
	v_mfma_f32_32x32x16_bf16 v[2:17], v[250:253], v[196:199], v[2:17]
	ds_read_b128 v[136:139], v178 offset:16384
	ds_read_b128 v[140:143], v178 offset:24576
	ds_read_b128 v[204:207], v181 offset:16384
	ds_read_b128 v[208:211], v181 offset:24576
	ds_read_b128 v[238:241], v180 offset:16384
	ds_read_b128 v[242:245], v180 offset:24576
	ds_read_b128 v[246:249], v179 offset:16384
	ds_read_b128 v[250:253], v179 offset:24576
	s_waitcnt vmcnt(6)
	s_add_i32 s50, s50, 64
	s_barrier
; #define LAS __attribute__((address_space(3)))
; __device__ __forceinline__ float max3f(float a, float b, float c) { float r; asm("v_max3_f32 %0, %1, %2, %3" : "=v"(r) : "v"(a), "v"(b), "v"(c)); return r; }
; __device__ __forceinline__ void attn_block(LAS unsigned char* lds, const bf16_t* P, bf16_t* mix, int b, int h, int qb, float lam, float outscale, const float* subln) {
;     ...
;         const int kb = 64 * kt;
;         if (kb <= qw0 + 31) {
;             LAS const unsigned char* Kb = lds + ATT_K0 + buf * 16384;
;             LAS const unsigned char* Vb = lds + ATT_V0 + buf * 16384;
;             f32x16 s0, s1;
; #pragma unroll
;             for (int j = 0; j < 16; ++j) { s0[j] = 0.f; s1[j] = 0.f; }
;             bf16x8 ka[4][2];
; #pragma unroll
;             for (int ks = 0; ks < 4; ++ks) { ka[ks][0] = *(const LAS bf16x8*)(Kb + kbase[ks]); ka[ks][1] = *(const LAS bf16x8*)(Kb + kbase[ks] + 8192); }
;             __builtin_amdgcn_sched_barrier(0);
; #pragma unroll
;             for (int ks = 0; ks < 4; ++ks) {
;                 s0 = __builtin_amdgcn_mfma_f32_32x32x16_bf16(ka[ks][0], qf[ks], s0, 0, 0, 0);
;                 s1 = __builtin_amdgcn_mfma_f32_32x32x16_bf16(ka[ks][1], qf[ks], s1, 0, 0, 0);
;             }
;             if (kb + 63 > qw0) {
; #pragma unroll
;                 for (int j = 0; j < 16; ++j) { const int key = kb + crow(j, hi); if (key > qrow) s0[j] = -INFINITY; if (key + 32 > qrow) s1[j] = -INFINITY; }
;             }
;             float mxa = max3f(s0[0], s1[0], s0[1]), mxb = max3f(s1[1], s0[2], s1[2]), mxc = max3f(s0[3], s1[3], s0[4]), mxd = max3f(s1[4], s0[5], s1[5]);
;             mxa = max3f(mxa, s0[6], s1[6]); mxb = max3f(mxb, s0[7], s1[7]); mxc = max3f(mxc, s0[8], s1[8]); mxd = max3f(mxd, s0[9], s1[9]);
;             mxa = max3f(mxa, s0[10], s1[10]); mxb = max3f(mxb, s0[11], s1[11]); mxc = max3f(mxc, s0[12], s1[12]); mxd = max3f(mxd, s0[13], s1[13]);
;             mxa = max3f(mxa, s0[14], s1[14]); mxb = max3f(mxb, s0[15], s1[15]);
;             float mx = max3f(mxa, mxb, max3f(mxc, mxd, mxd));
;             { auto rr = __builtin_amdgcn_permlane32_swap(__builtin_bit_cast(unsigned, mx), __builtin_bit_cast(unsigned, mx), false, false);
;               mx = fmaxf(__builtin_bit_cast(float, rr[0]), __builtin_bit_cast(float, rr[1])); }
;             if (__any(mx > mrun + 8.0f)) {
	s_add_i32 m0, s62, 0x0
	s_nop 0
	global_load_lds_dwordx4 v[134:135], off
	s_add_i32 m0, s62, 0x2000
	s_nop 0
	global_load_lds_dwordx4 v[200:201], off
	s_waitcnt lgkmcnt(6)
	v_mfma_f32_32x32x16_bf16 v[82:97], v[136:139], v[110:113], v[222:237]
	v_mfma_f32_32x32x16_bf16 v[66:81], v[140:143], v[110:113], v[222:237]
	s_waitcnt lgkmcnt(4)
	v_mfma_f32_32x32x16_bf16 v[82:97], v[204:207], v[106:109], v[82:97]
	v_mfma_f32_32x32x16_bf16 v[66:81], v[208:211], v[106:109], v[66:81]
	s_waitcnt lgkmcnt(2)
	v_mfma_f32_32x32x16_bf16 v[82:97], v[238:241], v[102:105], v[82:97]
	v_mfma_f32_32x32x16_bf16 v[66:81], v[242:245], v[102:105], v[66:81]
	s_waitcnt lgkmcnt(0)
	v_mfma_f32_32x32x16_bf16 v[82:97], v[246:249], v[98:101], v[82:97]
	v_mfma_f32_32x32x16_bf16 v[66:81], v[250:253], v[98:101], v[66:81]
	ds_read_b64_tr_b16 v[136:137], v168 offset:49152
	ds_read_b64_tr_b16 v[138:139], v175 offset:49152
	ds_read_b64_tr_b16 v[140:141], v172 offset:49152
	ds_read_b64_tr_b16 v[142:143], v174 offset:49152
	ds_read_b64_tr_b16 v[204:205], v170 offset:49152
	ds_read_b64_tr_b16 v[206:207], v173 offset:49152
	ds_read_b64_tr_b16 v[208:209], v169 offset:49152
	ds_read_b64_tr_b16 v[210:211], v171 offset:49152
	ds_read_b64_tr_b16 v[238:239], v168 offset:53248
	ds_read_b64_tr_b16 v[240:241], v175 offset:53248
	ds_read_b64_tr_b16 v[242:243], v172 offset:53248
	ds_read_b64_tr_b16 v[244:245], v174 offset:53248
	s_nop 1
	v_max3_f32 v122, v82, v66, v83
	v_max3_f32 v123, v67, v84, v68
	v_max3_f32 v124, v85, v69, v86
	v_max3_f32 v125, v70, v87, v71
	v_max3_f32 v122, v122, v88, v72
	v_max3_f32 v123, v123, v89, v73
	v_max3_f32 v124, v124, v90, v74
	v_max3_f32 v125, v125, v91, v75
	v_max3_f32 v122, v122, v92, v76
	v_max3_f32 v123, v123, v93, v77
	v_max3_f32 v124, v124, v94, v78
	v_max3_f32 v125, v125, v95, v79
	v_max3_f32 v122, v122, v96, v80
	v_max3_f32 v123, v123, v97, v81
	v_max3_f32 v122, v122, v123, v124
	v_max_f32_e32 v122, v122, v125
	v_mov_b32_e32 v203, v122
	s_nop 1
	v_permlane32_swap_b32_e32 v122, v203
	s_nop 1
	v_max_f32_e32 v122, v122, v203
	s_mov_b32 s39, 0
	v_cmp_lt_f32_e32 vcc, 0x41000000, v122
	s_cmp_eq_u32 s50, 0
	s_cbranch_scc1 .Lat2_u1_first
	s_cbranch_vccz .Lat2_u1_norescale
	s_branch .Lat2_u1_rescale

; #define LAS __attribute__((address_space(3)))
; __device__ __forceinline__ unsigned pk2(float lo, float hi) { f32x2 v = {lo, hi}; bf16x2_t b = __builtin_convertvector(v, bf16x2_t); return __builtin_bit_cast(unsigned, b); }
; __device__ __forceinline__ s16x4 vtr(LAS const unsigned char* p) { return __builtin_bit_cast(s16x4, __builtin_amdgcn_ds_read_tr16_b64_v4i16((LAS v4i16_t*)p)); }
; __device__ __forceinline__ bf16x8 cat8(s16x4 a, s16x4 b) { return (bf16x8){a[0], a[1], a[2], a[3], b[0], b[1], b[2], b[3]}; }
; __device__ __forceinline__ void attn_block(LAS unsigned char* lds, const bf16_t* P, bf16_t* mix, int b, int h, int qb, float lam, float outscale, const float* subln) {
;     ...
;             for (int ks = 0; ks < 4; ++ks) { ka[ks][0] = *(const LAS bf16x8*)(Kb + kbase[ks]); ka[ks][1] = *(const LAS bf16x8*)(Kb + kbase[ks] + 8192); }
;     ...
; #pragma unroll
;             for (int j = 0; j < 16; ++j) { s0[j] = __builtin_amdgcn_exp2f(s0[j] - mrun); s1[j] = __builtin_amdgcn_exp2f(s1[j] - mrun); }
;             float ps0 = 0.f, ps1 = 0.f, ps2 = 0.f, ps3 = 0.f;
; #pragma unroll
;             for (int j = 0; j < 16; j += 2) { ps0 += s0[j]; ps1 += s1[j]; ps2 += s0[j + 1]; ps3 += s1[j + 1]; }
;             lrun += (ps0 + ps1) + (ps2 + ps3);
;             bf16x8 pb[4];
; #pragma unroll
;             for (int s2 = 0; s2 < 2; ++s2) {
;                 u32x4 w0, w1;
;                 w0.x = pk2(s0[8 * s2 + 0], s0[8 * s2 + 1]); w0.y = pk2(s0[8 * s2 + 2], s0[8 * s2 + 3]); w0.z = pk2(s0[8 * s2 + 4], s0[8 * s2 + 5]); w0.w = pk2(s0[8 * s2 + 6], s0[8 * s2 + 7]);
;                 w1.x = pk2(s1[8 * s2 + 0], s1[8 * s2 + 1]); w1.y = pk2(s1[8 * s2 + 2], s1[8 * s2 + 3]); w1.z = pk2(s1[8 * s2 + 4], s1[8 * s2 + 5]); w1.w = pk2(s1[8 * s2 + 6], s1[8 * s2 + 7]);
;                 pb[s2] = __builtin_bit_cast(bf16x8, w0); pb[2 + s2] = __builtin_bit_cast(bf16x8, w1);
;             }
; #pragma unroll
;             for (int s = 0; s < 4; ++s) {
; #pragma unroll
;                 for (int c = 0; c < 4; ++c) {
;                     const s16x4 v0 = vtr(Vb + vbase[c][0] + 4096 * s);
;                     const s16x4 v1 = vtr(Vb + vbase[c][1] + 4096 * s);
;                     o[c] = __builtin_amdgcn_mfma_f32_32x32x16_bf16(cat8(v0, v1), pb[s], o[c], 0, 0, 0);
;                 }
;             }
.Lat2_u1_norescale:
	v_exp_f32_e32 v82, v82
	v_exp_f32_e32 v83, v83
	v_exp_f32_e32 v84, v84
	v_exp_f32_e32 v85, v85
	v_exp_f32_e32 v86, v86
	v_exp_f32_e32 v87, v87
	v_exp_f32_e32 v88, v88
	v_exp_f32_e32 v89, v89
	v_exp_f32_e32 v90, v90
	v_exp_f32_e32 v91, v91
	v_exp_f32_e32 v92, v92
	v_exp_f32_e32 v93, v93
	v_exp_f32_e32 v94, v94
	v_exp_f32_e32 v95, v95
	v_exp_f32_e32 v96, v96
	v_exp_f32_e32 v97, v97
	v_cvt_pk_bf16_f32 v184, v82, v83
	v_cvt_pk_bf16_f32 v185, v84, v85
	v_cvt_pk_bf16_f32 v186, v86, v87
	v_cvt_pk_bf16_f32 v187, v88, v89
	v_cvt_pk_bf16_f32 v188, v90, v91
	v_cvt_pk_bf16_f32 v189, v92, v93
	v_cvt_pk_bf16_f32 v190, v94, v95
	v_cvt_pk_bf16_f32 v191, v96, v97
	v_add_f32_e32 v122, v82, v83
	v_add_f32_e32 v123, v84, v85
	v_add_f32_e32 v122, v122, v86
	v_add_f32_e32 v123, v123, v87
	v_add_f32_e32 v122, v122, v88
	v_add_f32_e32 v123, v123, v89
	v_add_f32_e32 v122, v122, v123
	v_add_f32_e32 v167, v167, v122
	v_add_f32_e32 v124, v90, v91
	v_add_f32_e32 v125, v92, v93
	v_add_f32_e32 v124, v124, v94
	v_add_f32_e32 v125, v125, v95
	v_add_f32_e32 v124, v124, v96
	v_add_f32_e32 v125, v125, v97
	v_add_f32_e32 v124, v124, v125
	v_add_f32_e32 v167, v167, v124
	s_add_i32 m0, s62, 0x7800
	s_nop 0
	global_load_lds_dwordx4 v[134:135], off offset:2048
	s_add_i32 m0, s62, 0x9800
	s_nop 0
	global_load_lds_dwordx4 v[200:201], off offset:2048
	v_lshl_add_u64 v[134:135], v[134:135], 0, s[40:41]
	v_lshl_add_u64 v[200:201], v[200:201], 0, s[40:41]
	s_waitcnt lgkmcnt(8)
	v_mfma_f32_32x32x16_bf16 v[50:65], v[136:139], v[184:187], v[50:65]
	ds_read_b64_tr_b16 v[246:247], v170 offset:53248
	ds_read_b64_tr_b16 v[248:249], v173 offset:53248
	v_exp_f32_e32 v66, v66
	v_exp_f32_e32 v67, v67
	v_exp_f32_e32 v68, v68
	v_mfma_f32_32x32x16_bf16 v[34:49], v[140:143], v[184:187], v[34:49]
	ds_read_b64_tr_b16 v[250:251], v169 offset:53248
	ds_read_b64_tr_b16 v[252:253], v171 offset:53248
	v_exp_f32_e32 v69, v69
	v_exp_f32_e32 v70, v70
	v_exp_f32_e32 v71, v71
	s_waitcnt lgkmcnt(8)
	v_mfma_f32_32x32x16_bf16 v[18:33], v[204:207], v[184:187], v[18:33]
	ds_read_b64_tr_b16 v[136:137], v168 offset:57344
	ds_read_b64_tr_b16 v[138:139], v175 offset:57344
	v_exp_f32_e32 v72, v72
	v_exp_f32_e32 v73, v73
	v_cvt_pk_bf16_f32 v192, v66, v67
	v_mfma_f32_32x32x16_bf16 v[2:17], v[208:211], v[184:187], v[2:17]
	ds_read_b64_tr_b16 v[140:141], v172 offset:57344
	ds_read_b64_tr_b16 v[142:143], v174 offset:57344
	v_cvt_pk_bf16_f32 v193, v68, v69
	v_cvt_pk_bf16_f32 v194, v70, v71
	v_cvt_pk_bf16_f32 v195, v72, v73
	s_waitcnt lgkmcnt(8)
	v_mfma_f32_32x32x16_bf16 v[50:65], v[238:241], v[188:191], v[50:65]
	ds_read_b64_tr_b16 v[204:205], v170 offset:57344
	ds_read_b64_tr_b16 v[206:207], v173 offset:57344
	v_exp_f32_e32 v74, v74
	v_exp_f32_e32 v75, v75
	v_exp_f32_e32 v76, v76
	v_mfma_f32_32x32x16_bf16 v[34:49], v[242:245], v[188:191], v[34:49]
	ds_read_b64_tr_b16 v[208:209], v169 offset:57344
	ds_read_b64_tr_b16 v[210:211], v171 offset:57344
	v_exp_f32_e32 v77, v77
	v_exp_f32_e32 v78, v78
	v_exp_f32_e32 v79, v79
	s_waitcnt lgkmcnt(8)
	v_mfma_f32_32x32x16_bf16 v[18:33], v[246:249], v[188:191], v[18:33]
	ds_read_b64_tr_b16 v[238:239], v168 offset:61440
	ds_read_b64_tr_b16 v[240:241], v175 offset:61440
	v_exp_f32_e32 v80, v80
	v_exp_f32_e32 v81, v81
	v_cvt_pk_bf16_f32 v196, v74, v75
	v_mfma_f32_32x32x16_bf16 v[2:17], v[250:253], v[188:191], v[2:17]
	ds_read_b64_tr_b16 v[242:243], v172 offset:61440
	ds_read_b64_tr_b16 v[244:245], v174 offset:61440
	v_cvt_pk_bf16_f32 v197, v76, v77
	v_cvt_pk_bf16_f32 v198, v78, v79
	v_cvt_pk_bf16_f32 v199, v80, v81
	s_waitcnt lgkmcnt(8)
	v_mfma_f32_32x32x16_bf16 v[50:65], v[136:139], v[192:195], v[50:65]
	ds_read_b64_tr_b16 v[246:247], v170 offset:61440
	ds_read_b64_tr_b16 v[248:249], v173 offset:61440
	v_add_f32_e32 v0, v66, v67
	v_add_f32_e32 v203, v68, v69
	v_add_f32_e32 v0, v0, v70
	v_mfma_f32_32x32x16_bf16 v[34:49], v[140:143], v[192:195], v[34:49]
	ds_read_b64_tr_b16 v[250:251], v169 offset:61440
	ds_read_b64_tr_b16 v[252:253], v171 offset:61440
	v_add_f32_e32 v203, v203, v71
	v_add_f32_e32 v0, v0, v72
	v_add_f32_e32 v203, v203, v73
	s_waitcnt lgkmcnt(8)
	v_mfma_f32_32x32x16_bf16 v[18:33], v[204:207], v[192:195], v[18:33]
	v_add_f32_e32 v0, v0, v203
	v_add_f32_e32 v167, v167, v0
	v_add_f32_e32 v0, v74, v75
	v_mfma_f32_32x32x16_bf16 v[2:17], v[208:211], v[192:195], v[2:17]
	v_add_f32_e32 v203, v76, v77
	v_add_f32_e32 v0, v0, v78
	v_add_f32_e32 v203, v203, v79
	s_waitcnt lgkmcnt(4)
	v_mfma_f32_32x32x16_bf16 v[50:65], v[238:241], v[196:199], v[50:65]
	v_add_f32_e32 v0, v0, v80
	v_add_f32_e32 v203, v203, v81
	v_add_f32_e32 v0, v0, v203
	v_mfma_f32_32x32x16_bf16 v[34:49], v[242:245], v[196:199], v[34:49]
	v_add_f32_e32 v167, v167, v0
	s_waitcnt lgkmcnt(0)
	v_mfma_f32_32x32x16_bf16 v[18:33], v[246:249], v[196:199], v[18:33]
	v_mfma_f32_32x32x16_bf16 v[2:17], v[250:253], v[196:199], v[2:17]
	ds_read_b128 v[136:139], v126 offset:0
	ds_read_b128 v[140:143], v126 offset:8192
	ds_read_b128 v[204:207], v127 offset:0
	ds_read_b128 v[208:211], v127 offset:8192
	ds_read_b128 v[238:241], v128 offset:0
	ds_read_b128 v[242:245], v128 offset:8192
	ds_read_b128 v[246:249], v129 offset:0
	ds_read_b128 v[250:253], v129 offset:8192
	s_waitcnt vmcnt(6)
	s_add_i32 s50, s50, 64
	s_barrier
; #define LAS __attribute__((address_space(3)))
; __device__ __forceinline__ float max3f(float a, float b, float c) { float r; asm("v_max3_f32 %0, %1, %2, %3" : "=v"(r) : "v"(a), "v"(b), "v"(c)); return r; }
; __device__ __forceinline__ void attn_block(LAS unsigned char* lds, const bf16_t* P, bf16_t* mix, int b, int h, int qb, float lam, float outscale, const float* subln) {
;     ...
;         const int kb = 64 * kt;
;         if (kb <= qw0 + 31) {
;             LAS const unsigned char* Kb = lds + ATT_K0 + buf * 16384;
;             LAS const unsigned char* Vb = lds + ATT_V0 + buf * 16384;
;             f32x16 s0, s1;
; #pragma unroll
;             for (int j = 0; j < 16; ++j) { s0[j] = 0.f; s1[j] = 0.f; }
;             bf16x8 ka[4][2];
; #pragma unroll
;             for (int ks = 0; ks < 4; ++ks) { ka[ks][0] = *(const LAS bf16x8*)(Kb + kbase[ks]); ka[ks][1] = *(const LAS bf16x8*)(Kb + kbase[ks] + 8192); }
;             __builtin_amdgcn_sched_barrier(0);
; #pragma unroll
;             for (int ks = 0; ks < 4; ++ks) {
;                 s0 = __builtin_amdgcn_mfma_f32_32x32x16_bf16(ka[ks][0], qf[ks], s0, 0, 0, 0);
;                 s1 = __builtin_amdgcn_mfma_f32_32x32x16_bf16(ka[ks][1], qf[ks], s1, 0, 0, 0);
;             }
;             if (kb + 63 > qw0) {
; #pragma unroll
;                 for (int j = 0; j < 16; ++j) { const int key = kb + crow(j, hi); if (key > qrow) s0[j] = -INFINITY; if (key + 32 > qrow) s1[j] = -INFINITY; }
;             }
;             float mxa = max3f(s0[0], s1[0], s0[1]), mxb = max3f(s1[1], s0[2], s1[2]), mxc = max3f(s0[3], s1[3], s0[4]), mxd = max3f(s1[4], s0[5], s1[5]);
;             mxa = max3f(mxa, s0[6], s1[6]); mxb = max3f(mxb, s0[7], s1[7]); mxc = max3f(mxc, s0[8], s1[8]); mxd = max3f(mxd, s0[9], s1[9]);
;             mxa = max3f(mxa, s0[10], s1[10]); mxb = max3f(mxb, s0[11], s1[11]); mxc = max3f(mxc, s0[12], s1[12]); mxd = max3f(mxd, s0[13], s1[13]);
;             mxa = max3f(mxa, s0[14], s1[14]); mxb = max3f(mxb, s0[15], s1[15]);
;             float mx = max3f(mxa, mxb, max3f(mxc, mxd, mxd));
;             { auto rr = __builtin_amdgcn_permlane32_swap(__builtin_bit_cast(unsigned, mx), __builtin_bit_cast(unsigned, mx), false, false);
;               mx = fmaxf(__builtin_bit_cast(float, rr[0]), __builtin_bit_cast(float, rr[1])); }
;             if (__any(mx > mrun + 8.0f)) {
	s_add_i32 m0, s62, 0x4000
	s_nop 0
	global_load_lds_dwordx4 v[134:135], off
	s_add_i32 m0, s62, 0x6000
	s_nop 0
	global_load_lds_dwordx4 v[200:201], off
	s_waitcnt lgkmcnt(6)
	v_mfma_f32_32x32x16_bf16 v[82:97], v[136:139], v[110:113], v[222:237]
	v_mfma_f32_32x32x16_bf16 v[66:81], v[140:143], v[110:113], v[222:237]
	s_waitcnt lgkmcnt(4)
	v_mfma_f32_32x32x16_bf16 v[82:97], v[204:207], v[106:109], v[82:97]
	v_mfma_f32_32x32x16_bf16 v[66:81], v[208:211], v[106:109], v[66:81]
	s_waitcnt lgkmcnt(2)
	v_mfma_f32_32x32x16_bf16 v[82:97], v[238:241], v[102:105], v[82:97]
	v_mfma_f32_32x32x16_bf16 v[66:81], v[242:245], v[102:105], v[66:81]
	s_waitcnt lgkmcnt(0)
	v_mfma_f32_32x32x16_bf16 v[82:97], v[246:249], v[98:101], v[82:97]
	v_mfma_f32_32x32x16_bf16 v[66:81], v[250:253], v[98:101], v[66:81]
	ds_read_b64_tr_b16 v[136:137], v114 offset:32768
	ds_read_b64_tr_b16 v[138:139], v115 offset:32768
	ds_read_b64_tr_b16 v[140:141], v116 offset:32768
	ds_read_b64_tr_b16 v[142:143], v117 offset:32768
	ds_read_b64_tr_b16 v[204:205], v118 offset:32768
	ds_read_b64_tr_b16 v[206:207], v119 offset:32768
	ds_read_b64_tr_b16 v[208:209], v120 offset:32768
	ds_read_b64_tr_b16 v[210:211], v121 offset:32768
	ds_read_b64_tr_b16 v[238:239], v114 offset:36864
	ds_read_b64_tr_b16 v[240:241], v115 offset:36864
	ds_read_b64_tr_b16 v[242:243], v116 offset:36864
	ds_read_b64_tr_b16 v[244:245], v117 offset:36864
	s_nop 1
	v_max3_f32 v122, v82, v66, v83
	v_max3_f32 v123, v67, v84, v68
	v_max3_f32 v124, v85, v69, v86
	v_max3_f32 v125, v70, v87, v71
	v_max3_f32 v122, v122, v88, v72
	v_max3_f32 v123, v123, v89, v73
	v_max3_f32 v124, v124, v90, v74
	v_max3_f32 v125, v125, v91, v75
	v_max3_f32 v122, v122, v92, v76
	v_max3_f32 v123, v123, v93, v77
	v_max3_f32 v124, v124, v94, v78
	v_max3_f32 v125, v125, v95, v79
	v_max3_f32 v122, v122, v96, v80
	v_max3_f32 v123, v123, v97, v81
	v_max3_f32 v122, v122, v123, v124
	v_max_f32_e32 v122, v122, v125
	v_mov_b32_e32 v203, v122
	s_nop 1
	v_permlane32_swap_b32_e32 v122, v203
	s_nop 1
	v_max_f32_e32 v122, v122, v203
	s_mov_b32 s39, 0
	v_cmp_lt_f32_e32 vcc, 0x41000000, v122
	s_cmp_eq_u32 s50, 0
	s_cbranch_scc1 .Lat2_u2_first
	s_cbranch_vccz .Lat2_u2_norescale
	s_branch .Lat2_u2_rescale

; #define LAS __attribute__((address_space(3)))
; __device__ __forceinline__ unsigned pk2(float lo, float hi) { f32x2 v = {lo, hi}; bf16x2_t b = __builtin_convertvector(v, bf16x2_t); return __builtin_bit_cast(unsigned, b); }
; __device__ __forceinline__ s16x4 vtr(LAS const unsigned char* p) { return __builtin_bit_cast(s16x4, __builtin_amdgcn_ds_read_tr16_b64_v4i16((LAS v4i16_t*)p)); }
; __device__ __forceinline__ bf16x8 cat8(s16x4 a, s16x4 b) { return (bf16x8){a[0], a[1], a[2], a[3], b[0], b[1], b[2], b[3]}; }
; __device__ __forceinline__ void attn_block(LAS unsigned char* lds, const bf16_t* P, bf16_t* mix, int b, int h, int qb, float lam, float outscale, const float* subln) {
;     ...
;             for (int ks = 0; ks < 4; ++ks) { ka[ks][0] = *(const LAS bf16x8*)(Kb + kbase[ks]); ka[ks][1] = *(const LAS bf16x8*)(Kb + kbase[ks] + 8192); }
;     ...
; #pragma unroll
;             for (int j = 0; j < 16; ++j) { s0[j] = __builtin_amdgcn_exp2f(s0[j] - mrun); s1[j] = __builtin_amdgcn_exp2f(s1[j] - mrun); }
;             float ps0 = 0.f, ps1 = 0.f, ps2 = 0.f, ps3 = 0.f;
; #pragma unroll
;             for (int j = 0; j < 16; j += 2) { ps0 += s0[j]; ps1 += s1[j]; ps2 += s0[j + 1]; ps3 += s1[j + 1]; }
;             lrun += (ps0 + ps1) + (ps2 + ps3);
;             bf16x8 pb[4];
; #pragma unroll
;             for (int s2 = 0; s2 < 2; ++s2) {
;                 u32x4 w0, w1;
;                 w0.x = pk2(s0[8 * s2 + 0], s0[8 * s2 + 1]); w0.y = pk2(s0[8 * s2 + 2], s0[8 * s2 + 3]); w0.z = pk2(s0[8 * s2 + 4], s0[8 * s2 + 5]); w0.w = pk2(s0[8 * s2 + 6], s0[8 * s2 + 7]);
;                 w1.x = pk2(s1[8 * s2 + 0], s1[8 * s2 + 1]); w1.y = pk2(s1[8 * s2 + 2], s1[8 * s2 + 3]); w1.z = pk2(s1[8 * s2 + 4], s1[8 * s2 + 5]); w1.w = pk2(s1[8 * s2 + 6], s1[8 * s2 + 7]);
;                 pb[s2] = __builtin_bit_cast(bf16x8, w0); pb[2 + s2] = __builtin_bit_cast(bf16x8, w1);
;             }
; #pragma unroll
;             for (int s = 0; s < 4; ++s) {
; #pragma unroll
;                 for (int c = 0; c < 4; ++c) {
;                     const s16x4 v0 = vtr(Vb + vbase[c][0] + 4096 * s);
;                     const s16x4 v1 = vtr(Vb + vbase[c][1] + 4096 * s);
;                     o[c] = __builtin_amdgcn_mfma_f32_32x32x16_bf16(cat8(v0, v1), pb[s], o[c], 0, 0, 0);
;                 }
;             }
.Lat2_u2_norescale:
	v_exp_f32_e32 v82, v82
	v_exp_f32_e32 v83, v83
	v_exp_f32_e32 v84, v84
	v_exp_f32_e32 v85, v85
	v_exp_f32_e32 v86, v86
	v_exp_f32_e32 v87, v87
	v_exp_f32_e32 v88, v88
	v_exp_f32_e32 v89, v89
	v_exp_f32_e32 v90, v90
	v_exp_f32_e32 v91, v91
	v_exp_f32_e32 v92, v92
	v_exp_f32_e32 v93, v93
	v_exp_f32_e32 v94, v94
	v_exp_f32_e32 v95, v95
	v_exp_f32_e32 v96, v96
	v_exp_f32_e32 v97, v97
	v_cvt_pk_bf16_f32 v184, v82, v83
	v_cvt_pk_bf16_f32 v185, v84, v85
	v_cvt_pk_bf16_f32 v186, v86, v87
	v_cvt_pk_bf16_f32 v187, v88, v89
	v_cvt_pk_bf16_f32 v188, v90, v91
	v_cvt_pk_bf16_f32 v189, v92, v93
	v_cvt_pk_bf16_f32 v190, v94, v95
	v_cvt_pk_bf16_f32 v191, v96, v97
	v_add_f32_e32 v122, v82, v83
	v_add_f32_e32 v123, v84, v85
	v_add_f32_e32 v122, v122, v86
	v_add_f32_e32 v123, v123, v87
	v_add_f32_e32 v122, v122, v88
	v_add_f32_e32 v123, v123, v89
	v_add_f32_e32 v122, v122, v123
	v_add_f32_e32 v167, v167, v122
	v_add_f32_e32 v124, v90, v91
	v_add_f32_e32 v125, v92, v93
	v_add_f32_e32 v124, v124, v94
	v_add_f32_e32 v125, v125, v95
	v_add_f32_e32 v124, v124, v96
	v_add_f32_e32 v125, v125, v97
	v_add_f32_e32 v124, v124, v125
	v_add_f32_e32 v167, v167, v124
	s_add_i32 m0, s62, 0xb800
	s_nop 0
	global_load_lds_dwordx4 v[134:135], off offset:2048
	s_add_i32 m0, s62, 0xd800
	s_nop 0
	global_load_lds_dwordx4 v[200:201], off offset:2048
	v_lshl_add_u64 v[134:135], v[134:135], 0, s[40:41]
	v_lshl_add_u64 v[200:201], v[200:201], 0, s[40:41]
	s_waitcnt lgkmcnt(8)
	v_mfma_f32_32x32x16_bf16 v[50:65], v[136:139], v[184:187], v[50:65]
	ds_read_b64_tr_b16 v[246:247], v118 offset:36864
	ds_read_b64_tr_b16 v[248:249], v119 offset:36864
	v_exp_f32_e32 v66, v66
	v_exp_f32_e32 v67, v67
	v_exp_f32_e32 v68, v68
	v_mfma_f32_32x32x16_bf16 v[34:49], v[140:143], v[184:187], v[34:49]
	ds_read_b64_tr_b16 v[250:251], v120 offset:36864
	ds_read_b64_tr_b16 v[252:253], v121 offset:36864
	v_exp_f32_e32 v69, v69
	v_exp_f32_e32 v70, v70
	v_exp_f32_e32 v71, v71
	s_waitcnt lgkmcnt(8)
	v_mfma_f32_32x32x16_bf16 v[18:33], v[204:207], v[184:187], v[18:33]
	ds_read_b64_tr_b16 v[136:137], v114 offset:40960
	ds_read_b64_tr_b16 v[138:139], v115 offset:40960
	v_exp_f32_e32 v72, v72
	v_exp_f32_e32 v73, v73
	v_cvt_pk_bf16_f32 v192, v66, v67
	v_mfma_f32_32x32x16_bf16 v[2:17], v[208:211], v[184:187], v[2:17]
	ds_read_b64_tr_b16 v[140:141], v116 offset:40960
	ds_read_b64_tr_b16 v[142:143], v117 offset:40960
	v_cvt_pk_bf16_f32 v193, v68, v69
	v_cvt_pk_bf16_f32 v194, v70, v71
	v_cvt_pk_bf16_f32 v195, v72, v73
	s_waitcnt lgkmcnt(8)
	v_mfma_f32_32x32x16_bf16 v[50:65], v[238:241], v[188:191], v[50:65]
	ds_read_b64_tr_b16 v[204:205], v118 offset:40960
	ds_read_b64_tr_b16 v[206:207], v119 offset:40960
	v_exp_f32_e32 v74, v74
	v_exp_f32_e32 v75, v75
	v_exp_f32_e32 v76, v76
	v_mfma_f32_32x32x16_bf16 v[34:49], v[242:245], v[188:191], v[34:49]
	ds_read_b64_tr_b16 v[208:209], v120 offset:40960
	ds_read_b64_tr_b16 v[210:211], v121 offset:40960
	v_exp_f32_e32 v77, v77
	v_exp_f32_e32 v78, v78
	v_exp_f32_e32 v79, v79
	s_waitcnt lgkmcnt(8)
	v_mfma_f32_32x32x16_bf16 v[18:33], v[246:249], v[188:191], v[18:33]
	ds_read_b64_tr_b16 v[238:239], v114 offset:45056
	ds_read_b64_tr_b16 v[240:241], v115 offset:45056
	v_exp_f32_e32 v80, v80
	v_exp_f32_e32 v81, v81
	v_cvt_pk_bf16_f32 v196, v74, v75
	v_mfma_f32_32x32x16_bf16 v[2:17], v[250:253], v[188:191], v[2:17]
	ds_read_b64_tr_b16 v[242:243], v116 offset:45056
	ds_read_b64_tr_b16 v[244:245], v117 offset:45056
	v_cvt_pk_bf16_f32 v197, v76, v77
	v_cvt_pk_bf16_f32 v198, v78, v79
	v_cvt_pk_bf16_f32 v199, v80, v81
	s_waitcnt lgkmcnt(8)
	v_mfma_f32_32x32x16_bf16 v[50:65], v[136:139], v[192:195], v[50:65]
	ds_read_b64_tr_b16 v[246:247], v118 offset:45056
	ds_read_b64_tr_b16 v[248:249], v119 offset:45056
	v_add_f32_e32 v0, v66, v67
	v_add_f32_e32 v203, v68, v69
	v_add_f32_e32 v0, v0, v70
	v_mfma_f32_32x32x16_bf16 v[34:49], v[140:143], v[192:195], v[34:49]
	ds_read_b64_tr_b16 v[250:251], v120 offset:45056
	ds_read_b64_tr_b16 v[252:253], v121 offset:45056
	v_add_f32_e32 v203, v203, v71
	v_add_f32_e32 v0, v0, v72
	v_add_f32_e32 v203, v203, v73
	s_waitcnt lgkmcnt(8)
	v_mfma_f32_32x32x16_bf16 v[18:33], v[204:207], v[192:195], v[18:33]
	v_add_f32_e32 v0, v0, v203
	v_add_f32_e32 v167, v167, v0
	v_add_f32_e32 v0, v74, v75
	v_mfma_f32_32x32x16_bf16 v[2:17], v[208:211], v[192:195], v[2:17]
	v_add_f32_e32 v203, v76, v77
	v_add_f32_e32 v0, v0, v78
	v_add_f32_e32 v203, v203, v79
	s_waitcnt lgkmcnt(4)
	v_mfma_f32_32x32x16_bf16 v[50:65], v[238:241], v[196:199], v[50:65]
	v_add_f32_e32 v0, v0, v80
	v_add_f32_e32 v203, v203, v81
	v_add_f32_e32 v0, v0, v203
	v_mfma_f32_32x32x16_bf16 v[34:49], v[242:245], v[196:199], v[34:49]
	v_add_f32_e32 v167, v167, v0
	s_waitcnt lgkmcnt(0)
	v_mfma_f32_32x32x16_bf16 v[18:33], v[246:249], v[196:199], v[18:33]
	v_mfma_f32_32x32x16_bf16 v[2:17], v[250:253], v[196:199], v[2:17]
	ds_read_b128 v[136:139], v126 offset:16384
	ds_read_b128 v[140:143], v126 offset:24576
	ds_read_b128 v[204:207], v127 offset:16384
	ds_read_b128 v[208:211], v127 offset:24576
	ds_read_b128 v[238:241], v128 offset:16384
	ds_read_b128 v[242:245], v128 offset:24576
	ds_read_b128 v[246:249], v129 offset:16384
	ds_read_b128 v[250:253], v129 offset:24576
	s_waitcnt vmcnt(6)
	s_add_i32 s50, s50, 64
	s_barrier
; #define LAS __attribute__((address_space(3)))
; __device__ __forceinline__ float max3f(float a, float b, float c) { float r; asm("v_max3_f32 %0, %1, %2, %3" : "=v"(r) : "v"(a), "v"(b), "v"(c)); return r; }
; __device__ __forceinline__ void attn_block(LAS unsigned char* lds, const bf16_t* P, bf16_t* mix, int b, int h, int qb, float lam, float outscale, const float* subln) {
;     ...
;         const int kb = 64 * kt;
;         if (kb <= qw0 + 31) {
;             LAS const unsigned char* Kb = lds + ATT_K0 + buf * 16384;
;             LAS const unsigned char* Vb = lds + ATT_V0 + buf * 16384;
;             f32x16 s0, s1;
; #pragma unroll
;             for (int j = 0; j < 16; ++j) { s0[j] = 0.f; s1[j] = 0.f; }
;             bf16x8 ka[4][2];
; #pragma unroll
;             for (int ks = 0; ks < 4; ++ks) { ka[ks][0] = *(const LAS bf16x8*)(Kb + kbase[ks]); ka[ks][1] = *(const LAS bf16x8*)(Kb + kbase[ks] + 8192); }
;             __builtin_amdgcn_sched_barrier(0);
; #pragma unroll
;             for (int ks = 0; ks < 4; ++ks) {
;                 s0 = __builtin_amdgcn_mfma_f32_32x32x16_bf16(ka[ks][0], qf[ks], s0, 0, 0, 0);
;                 s1 = __builtin_amdgcn_mfma_f32_32x32x16_bf16(ka[ks][1], qf[ks], s1, 0, 0, 0);
;             }
;             if (kb + 63 > qw0) {
; #pragma unroll
;                 for (int j = 0; j < 16; ++j) { const int key = kb + crow(j, hi); if (key > qrow) s0[j] = -INFINITY; if (key + 32 > qrow) s1[j] = -INFINITY; }
;             }
;             float mxa = max3f(s0[0], s1[0], s0[1]), mxb = max3f(s1[1], s0[2], s1[2]), mxc = max3f(s0[3], s1[3], s0[4]), mxd = max3f(s1[4], s0[5], s1[5]);
;             mxa = max3f(mxa, s0[6], s1[6]); mxb = max3f(mxb, s0[7], s1[7]); mxc = max3f(mxc, s0[8], s1[8]); mxd = max3f(mxd, s0[9], s1[9]);
;             mxa = max3f(mxa, s0[10], s1[10]); mxb = max3f(mxb, s0[11], s1[11]); mxc = max3f(mxc, s0[12], s1[12]); mxd = max3f(mxd, s0[13], s1[13]);
;             mxa = max3f(mxa, s0[14], s1[14]); mxb = max3f(mxb, s0[15], s1[15]);
;             float mx = max3f(mxa, mxb, max3f(mxc, mxd, mxd));
;             { auto rr = __builtin_amdgcn_permlane32_swap(__builtin_bit_cast(unsigned, mx), __builtin_bit_cast(unsigned, mx), false, false);
;               mx = fmaxf(__builtin_bit_cast(float, rr[0]), __builtin_bit_cast(float, rr[1])); }
;             if (__any(mx > mrun + 8.0f)) {
	s_add_i32 m0, s62, 0x10000
	s_nop 0
	global_load_lds_dwordx4 v[134:135], off
	s_add_i32 m0, s62, 0x12000
	s_nop 0
	global_load_lds_dwordx4 v[200:201], off
	s_waitcnt lgkmcnt(6)
	v_mfma_f32_32x32x16_bf16 v[82:97], v[136:139], v[110:113], v[222:237]
	v_mfma_f32_32x32x16_bf16 v[66:81], v[140:143], v[110:113], v[222:237]
	s_waitcnt lgkmcnt(4)
	v_mfma_f32_32x32x16_bf16 v[82:97], v[204:207], v[106:109], v[82:97]
	v_mfma_f32_32x32x16_bf16 v[66:81], v[208:211], v[106:109], v[66:81]
	s_waitcnt lgkmcnt(2)
	v_mfma_f32_32x32x16_bf16 v[82:97], v[238:241], v[102:105], v[82:97]
	v_mfma_f32_32x32x16_bf16 v[66:81], v[242:245], v[102:105], v[66:81]
	s_waitcnt lgkmcnt(0)
	v_mfma_f32_32x32x16_bf16 v[82:97], v[246:249], v[98:101], v[82:97]
	v_mfma_f32_32x32x16_bf16 v[66:81], v[250:253], v[98:101], v[66:81]
	ds_read_b64_tr_b16 v[136:137], v114 offset:49152
	ds_read_b64_tr_b16 v[138:139], v115 offset:49152
	ds_read_b64_tr_b16 v[140:141], v116 offset:49152
	ds_read_b64_tr_b16 v[142:143], v117 offset:49152
	ds_read_b64_tr_b16 v[204:205], v118 offset:49152
	ds_read_b64_tr_b16 v[206:207], v119 offset:49152
	ds_read_b64_tr_b16 v[208:209], v120 offset:49152
	ds_read_b64_tr_b16 v[210:211], v121 offset:49152
	ds_read_b64_tr_b16 v[238:239], v114 offset:53248
	ds_read_b64_tr_b16 v[240:241], v115 offset:53248
	ds_read_b64_tr_b16 v[242:243], v116 offset:53248
	ds_read_b64_tr_b16 v[244:245], v117 offset:53248
	s_nop 1
	v_max3_f32 v122, v82, v66, v83
	v_max3_f32 v123, v67, v84, v68
	v_max3_f32 v124, v85, v69, v86
	v_max3_f32 v125, v70, v87, v71
	v_max3_f32 v122, v122, v88, v72
	v_max3_f32 v123, v123, v89, v73
	v_max3_f32 v124, v124, v90, v74
	v_max3_f32 v125, v125, v91, v75
	v_max3_f32 v122, v122, v92, v76
	v_max3_f32 v123, v123, v93, v77
	v_max3_f32 v124, v124, v94, v78
	v_max3_f32 v125, v125, v95, v79
	v_max3_f32 v122, v122, v96, v80
	v_max3_f32 v123, v123, v97, v81
	v_max3_f32 v122, v122, v123, v124
	v_max_f32_e32 v122, v122, v125
	v_mov_b32_e32 v203, v122
	s_nop 1
	v_permlane32_swap_b32_e32 v122, v203
	s_nop 1
	v_max_f32_e32 v122, v122, v203
	s_mov_b32 s39, 0
	v_cmp_lt_f32_e32 vcc, 0x41000000, v122
	s_cmp_eq_u32 s50, 0
	s_cbranch_scc1 .Lat2_u3_first
	s_cbranch_vccz .Lat2_u3_norescale
	s_branch .Lat2_u3_rescale

; __device__ __forceinline__ void xcd_barrier_complete(unsigned* bar, unsigned x, unsigned& nloc, unsigned& nx) {
;     const unsigned G = gridDim.x * gridDim.y * gridDim.z;
;     unsigned sum, cnt, mine, sp = 0u;
;     for (;;) {
;         sum = 0u; cnt = 0u; mine = 0u;
; #pragma unroll
;         for (unsigned j = 0; j < 16; ++j) { const unsigned c = xb_ld(&bar[XB_XCNT(j)]); sum += c; cnt += (c > 0u) ? 1u : 0u; mine = (j == x) ? c : mine; }
;         if (sum == G) break;
;         __builtin_amdgcn_s_sleep(1);
;         if ((++sp & 255u) == 0u) { if (xb_ld(&bar[XB_TMO])) break; if (sp > XB_SPIN_CAP) { atomicAdd(&bar[XB_TMO], 1u); break; } }
;     }
;     nloc = mine > 0u ? mine : 1u; nx = cnt > 0u ? cnt : 1u;
; }
; __device__ __forceinline__ void xcd_barrier(const XcdBarrier& b) {
;     asm volatile("s_waitcnt vmcnt(0)" ::: "memory");
;     __syncthreads();
;     if (threadIdx.x == 0) {
;         unsigned* bar = b.bar;
;         __builtin_amdgcn_s_waitcnt(0);
;         unsigned nloc = b.st[0], nx = b.st[1];
;         if (nloc == 0u) { xcd_barrier_complete(bar, b.x, nloc, nx); b.st[0] = nloc; b.st[1] = nx; }
;         const unsigned old = xb_add(&bar[XB_XSUB(b.x)], 1u);
;         const unsigned gen = old / nloc;
;         if (old + 1u == (gen + 1u) * nloc) {
;             __builtin_amdgcn_fence(__ATOMIC_RELEASE, "agent");
;             asm volatile("s_waitcnt vmcnt(0)" ::: "memory");
;             const unsigned og = xb_add(&bar[XB_TOP], 1u);
;             const unsigned tg = og / nx;
;             if (og + 1u == (tg + 1u) * nx) xb_add(&bar[XB_TOPGEN], 1u);
;             else XB_SPIN(xb_ld(&bar[XB_TOPGEN]) == tg, bar);
;             __builtin_amdgcn_fence(__ATOMIC_ACQUIRE, "agent");
;             xb_add(&bar[XB_XGEN(b.x)], 1u);
;             asm volatile("s_waitcnt vmcnt(0)" ::: "memory");
;         } else {
;             XB_SPIN(xb_ld(&bar[XB_XGEN(b.x)]) == gen, bar);
;             __builtin_amdgcn_fence(__ATOMIC_ACQUIRE, "agent");
;             asm volatile("s_waitcnt vmcnt(0)" ::: "memory");
;         }
;     }
;     __syncthreads();
; }
; __global__ void __launch_bounds__(512, 2) mega(Params p_arg) {
;     ...
;         if (ph + 1 < ph_hi) { if (ph == ph_lo) grid.sync(); else { xbar.bar = (unsigned*)(p.ws + WS_CTL); xcd_barrier(xbar); } }
.LBB0_233:
	s_and_b64 vcc, exec, s[0:1]
	s_cbranch_vccz .LBB0_10
	s_add_i32 s0, s34, 1
	s_cmp_ge_i32 s0, s81
	s_cbranch_scc1 .LBB0_10
	s_cmp_lg_u32 s34, s80
	s_mov_b64 s[0:1], -1
	s_waitcnt vmcnt(0)
	s_waitcnt vmcnt(0)
	s_barrier
	s_mov_b64 s[0:1], exec
	v_readlane_b32 s4, v254, 2
	v_readlane_b32 s5, v254, 3
	s_and_b64 s[4:5], s[0:1], s[4:5]
	s_mov_b64 exec, s[4:5]
	s_cbranch_execz .LBB0_387
	v_readlane_b32 s2, v254, 38
	s_waitcnt vmcnt(0) expcnt(0) lgkmcnt(0)
	s_nop 0
	v_mov_b32_e32 v0, s2
	ds_read_b32 v3, v0
	v_readlane_b32 s2, v254, 39
	s_waitcnt lgkmcnt(0)
	v_cmp_ne_u32_e32 vcc, 0, v3
	v_mov_b32_e32 v0, s2
	ds_read_b32 v2, v0
	s_cbranch_vccnz .LBB0_252
	s_add_u32 s4, s22, 0x2ad00200
	s_addc_u32 s5, s23, 0
	s_add_u32 s6, s22, 0x2ad00400
	s_addc_u32 s7, s23, 0
	s_add_u32 s8, s22, 0x2ad00500
	s_addc_u32 s9, s23, 0
	s_add_u32 s10, s22, 0x2ad00600
	s_addc_u32 s11, s23, 0
	s_add_u32 s12, s22, 0x2ad00700
	s_addc_u32 s13, s23, 0
	s_add_u32 s14, s22, 0x2ad00800
	s_addc_u32 s15, s23, 0
	s_add_u32 s16, s22, 0x2ad00900
	s_addc_u32 s17, s23, 0
	s_add_u32 s18, s22, 0x2ad00a00
	s_addc_u32 s19, s23, 0
	s_add_u32 s20, s22, 0x2ad00b00
	s_addc_u32 s21, s23, 0
	s_add_u32 s42, s22, 0x2ad00c00
	s_addc_u32 s43, s23, 0
	s_add_u32 s44, s22, 0x2ad00d00
	s_addc_u32 s45, s23, 0
	s_add_u32 s46, s22, 0x2ad00e00
	s_addc_u32 s47, s23, 0
	s_add_u32 s48, s22, 0x2ad00f00
	s_addc_u32 s49, s23, 0
	s_add_u32 s50, s22, 0x2ad01000
	s_addc_u32 s51, s23, 0
	s_add_u32 s52, s22, 0x2ad01100
	s_addc_u32 s53, s23, 0
	s_add_u32 s54, s22, 0x2ad01200
	s_addc_u32 s55, s23, 0
	s_add_u32 s56, s22, 0x2ad01300
	s_addc_u32 s57, s23, 0
	s_mov_b32 s2, 1
	s_branch .LBB0_240
